# v9 + NA attention K/V tiles prefetched two tiles ahead through a third LDS slot (counted vmcnt(4) at the loop top, slot = j mod 3); bit-identical
# speedup vs baseline: 1.0055x; 1.0055x over previous
; #define DMA_TILE(T) do { const AGAS char* kb_ = (const AGAS char*)Kh + (size_t)(T) * (KVBLK * LDK * 2); const AGAS char* v0_ = (const AGAS char*)V0h + (size_t)(T) * (KVBLK * LDK * 2); \
;     const AGAS char* v1_ = (const AGAS char*)V1h + (size_t)(T) * (KVBLK * LDK * 2); _Pragma("unroll") for (int i_ = 0; i_ < 6; ++i_) dma_piece(kb_, v0_, v1_, lds, (T) & 1, wid * 6 + i_, lane); } while (0)
; __device__ __forceinline__ void attn_body3n(const AGAS bf16* __restrict__ Qb, const AGAS bf16* __restrict__ Kh, const AGAS bf16* __restrict__ V0h, AGAS bf16* __restrict__ Ob, int ldo, int NT, Mod M, ALAS char* lds) {
;     ...
;   asm volatile("s_waitcnt vmcnt(0) lgkmcnt(0)" ::: "memory"); __builtin_amdgcn_s_barrier();
;   DMA_TILE(0);
;   for (int j = 0; j < NT; ++j) {
;     asm volatile("s_waitcnt vmcnt(0) lgkmcnt(0)" ::: "memory");
;     __builtin_amdgcn_s_barrier(); asm volatile("" ::: "memory");
;     if (j + 1 < NT) DMA_TILE(j + 1);
; template <int ch>
; __device__ __forceinline__ void chunk_body(const Args& a, LAS unsigned char* lds, const XcdBarrier& bar, const int G, const int bx, const int vcu, const int gw, const int NGW, const int tid, const int lane, const int wave) {
;     ...
;                 const int r0 = qb * 4; int kr0 = r0 - 4; kr0 = kr0 < 0 ? 0 : (kr0 > R - 8 ? R - 8 : kr0);
;                 const int NT = (R - kr0) < 12 ? (R - kr0) : 12;
;                 __syncthreads();
;                 for (int i = tid; i < 465; i += NWAVES * 64) tab[i] = ((const GAS float*)a.rpb)[h * 465 + i] * (1.0f / att::SCALE);
;                 const GAS bf16* Q = (const GAS bf16*)SEG + ((size_t)(24 + h) * TC + tok0 + qb * 256) * 128;
;                 const GAS bf16* K = (const GAS bf16*)SEG + ((size_t)(32 + h) * TC + tok0 + kr0 * 64) * 128;
;                 const GAS bf16* V = (const GAS bf16*)SEG + ((size_t)(40 + h) * TC + tok0 + kr0 * 64) * 128;
;                 GAS bf16* O = (GAS bf16*)ON + (tok0 + qb * 256) * DM + h * 128;
;                 att::Mod M; M.a0 = 0.f; M.a1 = 0.f; M.jd = 0; M.cen = 0; M.rq = r0 + (wave >> 1); { int t = M.rq - 4; M.rsq = t < 0 ? 0 : (t > R - 8 ? R - 8 : t); }
;                 M.kr0 = kr0; M.c = (wave & 1) * 32 + r32; { int t = M.c - 8; M.cs = t < 0 ? 0 : (t > 48 ? 48 : t); } M.hi = hi; M.tab = tab;
;                 M.tab = (const LAS float*)(lds + att::B3_WS + 2048);
;                 att::attn_body3n(Q, K, V, O, DM, NT, M, (LAS char*)lds);
.LBB0_378:
	s_min_u32 s83, s8, 11
	s_cmp_eq_u32 s88, 0
	s_cselect_b32 s83, 8, s83
	s_and_b32 s8, s14, 0x3fffffc0
	s_lshl_b32 s8, s8, 2
	s_add_i32 s82, s8, 0
	s_add_i32 s88, s88, s72
	s_add_i32 s82, s82, 0x18000
	s_add_u32 s84, s53, s4
	s_addc_u32 s85, s55, s5
	s_lshl_b32 s4, s7, 10
	s_add_i32 m0, s18, s4
	v_lshlrev_b32_e32 v13, 4, v2
	global_load_lds_dwordx4 v19, s[84:85]
	s_lshl_b32 s7, s15, 2
	v_lshlrev_b32_e32 v17, 1, v2
	v_and_b32_e32 v13, 0xc0, v13
	v_and_b32_e32 v3, 0x100, v3
	v_cmp_gt_u32_e64 s[4:5], 32, v2
	v_or3_b32 v2, s7, v5, v1
	v_lshl_or_b32 v5, v6, 4, v7
	v_and_or_b32 v6, v8, 51, v1
	v_and_or_b32 v1, v14, 51, v1
	v_med3_i32 v12, s88, 4, 60
	v_and_b32_e32 v17, 32, v17
	v_lshl_or_b32 v2, v2, 8, v4
	v_lshlrev_b32_e32 v1, 8, v1
	v_lshl_or_b32 v145, v15, 4, v16
	v_or3_b32 v0, v13, v3, v0
	v_mov_b32_e32 v14, v129
	v_mov_b32_e32 v15, v129
	v_add_u32_e32 v139, -4, v12
	v_add_u32_e32 v141, 4, v12
	v_lshl_or_b32 v142, v6, 8, v9
	v_lshl_or_b32 v143, v10, 4, v11
	v_or3_b32 v144, v1, v4, s42
	v_cndmask_b32_e64 v128, v2, v5, s[0:1]
	v_add3_u32 v146, v17, 0, v0
	v_mov_b32_e32 v0, v129
	v_mov_b32_e32 v1, v129
	v_mov_b32_e32 v2, v129
	v_mov_b32_e32 v3, v129
	v_mov_b32_e32 v4, v129
	v_mov_b32_e32 v5, v129
	v_mov_b32_e32 v6, v129
	v_mov_b32_e32 v7, v129
	v_mov_b32_e32 v8, v129
	v_mov_b32_e32 v9, v129
	v_mov_b32_e32 v10, v129
	v_mov_b32_e32 v11, v129
	v_mov_b32_e32 v12, v129
	v_mov_b32_e32 v13, v129
	v_mov_b64_e32 v[62:63], v[14:15]
	v_mov_b64_e32 v[46:47], v[14:15]
	v_mov_b64_e32 v[30:31], v[14:15]
	v_lshl_add_u32 v140, v136, 2, s82
	s_lshl_b32 s89, s6, 10
	s_mov_b32 s16, 0
	v_mov_b32_e32 v148, 0
	v_mov_b32_e32 v147, 0xf149f2ca
	v_mov_b64_e32 v[60:61], v[12:13]
	v_mov_b64_e32 v[58:59], v[10:11]
	v_mov_b64_e32 v[56:57], v[8:9]
	v_mov_b64_e32 v[54:55], v[6:7]
	v_mov_b64_e32 v[52:53], v[4:5]
	v_mov_b64_e32 v[50:51], v[2:3]
	v_mov_b64_e32 v[48:49], v[0:1]
	v_mov_b64_e32 v[44:45], v[12:13]
	v_mov_b64_e32 v[42:43], v[10:11]
	v_mov_b64_e32 v[40:41], v[8:9]
	v_mov_b64_e32 v[38:39], v[6:7]
	v_mov_b64_e32 v[36:37], v[4:5]
	v_mov_b64_e32 v[34:35], v[2:3]
	v_mov_b64_e32 v[32:33], v[0:1]
	v_mov_b64_e32 v[28:29], v[12:13]
	v_mov_b64_e32 v[26:27], v[10:11]
	v_mov_b64_e32 v[24:25], v[8:9]
	v_mov_b64_e32 v[22:23], v[6:7]
	v_mov_b64_e32 v[20:21], v[4:5]
	v_mov_b64_e32 v[18:19], v[2:3]
	v_mov_b64_e32 v[16:17], v[0:1]
	s_waitcnt vmcnt(0)
	s_mov_b32 s98, 0
.LBB0_379:
	s_add_i32 s58, s16, 1
	s_cmp_ge_u32 s58, s83
	s_cbranch_scc1 .Lna_w0_0
	s_waitcnt vmcnt(4) lgkmcnt(0)
	s_branch .Lna_w1_0

; #define ALAS __attribute__((address_space(3)))
; #define AGAS __attribute__((address_space(1)))
; #define DMA_TILE(T) do { const AGAS char* kb_ = (const AGAS char*)Kh + (size_t)(T) * (KVBLK * LDK * 2); const AGAS char* v0_ = (const AGAS char*)V0h + (size_t)(T) * (KVBLK * LDK * 2); \
;     const AGAS char* v1_ = (const AGAS char*)V1h + (size_t)(T) * (KVBLK * LDK * 2); _Pragma("unroll") for (int i_ = 0; i_ < 6; ++i_) dma_piece(kb_, v0_, v1_, lds, (T) & 1, wid * 6 + i_, lane); } while (0)
; #define DMA_TILE(T) do { const AGAS char* kb_ = (const AGAS char*)Kh + (size_t)(T) * (KVBLK * LDK * 2); const AGAS char* v0_ = (const AGAS char*)V0h + (size_t)(T) * (KVBLK * LDK * 2); \
;     _Pragma("unroll") for (int i_ = 0; i_ < 4; ++i_) dma_piece(kb_, v0_, v0_, lds, (T) & 1, wid * 4 + i_, lane); } while (0)
; __device__ __forceinline__ void dma_piece(const AGAS char* Kb, const AGAS char* V0b, const AGAS char* V1b, ALAS char* lds, int buf, int pc, int lane) {
;   const int img = pc >> 4, pp = pc & 15, q = pp * 64 + lane;
;   unsigned goff; const AGAS char* gb; ALAS char* dst;
;   if (img == 0) { const int row = q >> 4, ch = (q & 15) ^ (row & 7); goff = (unsigned)(row * (LDK * 2) + ch * 16); gb = Kb; dst = lds + B3_K + buf * 16384 + pp * 1024; }
;   else { const int sub = q >> 5, within = q & 31, kk = (sub >> 2) * 8 + (within >> 2), k = (kk & ~0xC) | ((kk & 4) << 1) | ((kk & 8) >> 1), c = (sub & 3) * 32 + (within & 3) * 8;
;          goff = (unsigned)(k * (LDK * 2) + c * 2); gb = img == 1 ? V0b : V1b; dst = lds + B3_V + buf * 32768 + (img - 1) * 16384 + pp * 1024; }
;   __builtin_amdgcn_global_load_lds((const AGAS unsigned*)(gb + goff), (ALAS unsigned*)dst, 16, 0, 0);
; __device__ __forceinline__ void attn_body3n(const AGAS bf16* __restrict__ Qb, const AGAS bf16* __restrict__ Kh, const AGAS bf16* __restrict__ V0h, AGAS bf16* __restrict__ Ob, int ldo, int NT, Mod M, ALAS char* lds) {
;     ...
;   asm volatile("s_waitcnt vmcnt(0) lgkmcnt(0)" ::: "memory"); __builtin_amdgcn_s_barrier();
;   DMA_TILE(0);
;   for (int j = 0; j < NT; ++j) {
;     asm volatile("s_waitcnt vmcnt(0) lgkmcnt(0)" ::: "memory");
;     __builtin_amdgcn_s_barrier(); asm volatile("" ::: "memory");
;     if (j + 1 < NT) DMA_TILE(j + 1);
.Lna_w1_0:
	s_barrier
	s_add_i32 s100, s16, 2
	s_mov_b32 s101, 0
	s_cmp_eq_u32 s16, 0
	s_cbranch_scc0 .Lna_blk_0
	s_mov_b32 s100, 1
.Lna_blk_0:
	s_cmp_ge_u32 s100, s83
	s_cbranch_scc1 .LBB0_385
	s_mul_i32 s99, s100, 11
	s_lshr_b32 s99, s99, 5
	s_mul_i32 s99, s99, 3
	s_sub_i32 s99, s100, s99
	s_lshl_b32 s7, s99, 15
	s_lshl_b32 s6, s99, 14
	s_cmp_eq_u32 s99, 2
	s_cselect_b32 s7, 0xc000, s7
	s_cselect_b32 s6, 0xffff4000, s6
	s_add_i32 s7, s46, s7
	s_add_i32 s18, s6, 0
	s_lshl_b64 s[8:9], s[100:101], 14
	s_add_i32 s17, s7, 0xffffc000
	s_add_i32 s18, s18, 0x10000
	s_and_b64 s[6:7], s[0:1], exec
	s_cselect_b32 s19, s18, s17
	s_add_u32 s12, s84, s8
	s_addc_u32 s13, s85, s9
	s_add_i32 m0, s19, s89
	v_lshl_add_u64 v[64:65], s[12:13], 0, v[128:129]
	global_load_lds_dwordx4 v[64:65], off
	v_cndmask_b32_e64 v64, 0, 1, s[0:1]
	v_cmp_ne_u32_e64 s[6:7], 1, v64
	s_andn2_b64 vcc, exec, s[0:1]
	v_mov_b32_e32 v64, v144
	s_mov_b32 s20, s56
	s_mov_b32 s21, s52
	s_mov_b32 s22, s17
	s_mov_b64 s[14:15], s[80:81]
	v_mov_b32_e32 v65, v142
	s_cbranch_vccnz .LBB0_382
	v_mov_b32_e32 v64, v145
	s_mov_b32 s20, s54
	s_mov_b32 s21, s47
	s_mov_b32 s22, s18
	s_mov_b64 s[14:15], s[78:79]
	v_mov_b32_e32 v65, v143

; #define ALAS __attribute__((address_space(3)))
; __device__ __forceinline__ void qkt(f32x16& p0, f32x16& p1, const ALAS char* Ks, const bf16x8* qr, int r32, int hi) {
;   p0 = f32x16{}; p1 = f32x16{};
; #pragma unroll
;   for (int d0 = 0; d0 < 8; ++d0) { int cb = (d0 * 16 + hi * 8) * 2;
;     bf16x8 b0 = *(const ALAS bf16x8*)(Ks + KSWZ(r32, cb));
;     bf16x8 b1 = *(const ALAS bf16x8*)(Ks + KSWZ(32 + r32, cb));
;     p0 = __builtin_amdgcn_mfma_f32_32x32x16_bf16(b0, qr[d0], p0, 0, 0, 0);
;     p1 = __builtin_amdgcn_mfma_f32_32x32x16_bf16(b1, qr[d0], p1, 0, 0, 0); }
; }
; __device__ __forceinline__ void attn_body3n(const AGAS bf16* __restrict__ Qb, const AGAS bf16* __restrict__ Kh, const AGAS bf16* __restrict__ V0h, AGAS bf16* __restrict__ Ob, int ldo, int NT, Mod M, ALAS char* lds) {
;     ...
;     { const int kr = M.kr0 + j; if (!(kr >= M.rsq && kr < M.rsq + 8)) continue; }
;     f32x16 p0, p1; bf16x8 pa0, pa1, pa2, pa3;
;     { int r32m = r32, him = hi; asm volatile("" : "+v"(r32m), "+v"(him)); qkt(p0, p1, lds + B3_K + (j & 1) * 16384, qr, r32m, him); }
;     float mn, alpha, bo0; { Mod Mv = M; asm volatile("" : "+v"(Mv.c), "+v"(Mv.cs), "+v"(Mv.hi)); modify<1>(p0, p1, Mv, j, bo0); }
.LBB0_384:
	s_add_u32 s6, s53, s6
	s_addc_u32 s7, s55, s7
	s_add_u32 s6, s6, s8
	s_addc_u32 s7, s7, s9
	s_lshl_b32 s8, s12, 10
	s_add_i32 m0, s17, s8
	s_nop 0
	global_load_lds_dwordx4 v64, s[6:7]
	s_cmp_eq_u32 s16, 0
	s_cbranch_scc0 .LBB0_385
	s_cmp_eq_u32 s100, 1
	s_cbranch_scc0 .LBB0_385
	s_mov_b32 s100, 2
	s_branch .Lna_blk_0
.LBB0_385:
	s_add_i32 s8, s16, s45
	v_cmp_ge_i32_e32 vcc, s8, v139
	v_cmp_lt_i32_e64 s[6:7], s8, v141
	s_and_b64 s[6:7], vcc, s[6:7]
	s_andn2_b64 vcc, exec, s[6:7]
	s_cbranch_vccnz .LBB0_424
	s_lshl_b32 s90, s98, 15
	v_mov_b32_e32 v64, v137
	v_mov_b32_e32 v65, v136
	s_lshl_b32 s6, s98, 14
	s_cmp_eq_u32 s98, 2
	s_cselect_b32 s90, 0xc000, s90
	s_cselect_b32 s6, 0xffff4000, s6
	s_add_i32 s6, s6, 0
	s_add_i32 s6, s6, 0x10000
	v_lshlrev_b32_e32 v149, 4, v64
	v_lshlrev_b32_e32 v158, 4, v65
	v_and_b32_e32 v158, 0x70, v158
	v_lshl_add_u32 v159, v65, 8, s6
	v_xad_u32 v150, v149, v158, v159
	v_add_u32_e32 v247, 32, v149
	v_xad_u32 v151, v247, v158, v159
	v_add_u32_e32 v247, 64, v149
	v_xad_u32 v152, v247, v158, v159
	v_add_u32_e32 v247, 0x60, v149
	v_xad_u32 v153, v247, v158, v159
	s_sub_i32 s6, s8, s88
	s_mul_i32 s6, s6, 31
	s_movk_i32 s8, 0xffe0
	ds_read_b128 v[208:211], v150
	ds_read_b128 v[212:215], v150 offset:8192
	ds_read_b128 v[216:219], v151
	ds_read_b128 v[220:223], v151 offset:8192
	ds_read_b128 v[224:227], v152
	ds_read_b128 v[228:231], v152 offset:8192
	s_waitcnt lgkmcnt(5)
	v_mfma_f32_32x32x16_bf16 v[80:95], v[208:211], v[96:99], 0
	ds_read_b128 v[208:211], v153
	s_waitcnt lgkmcnt(5)
	v_mfma_f32_32x32x16_bf16 v[64:79], v[212:215], v[96:99], 0
	ds_read_b128 v[212:215], v153 offset:8192
	s_waitcnt lgkmcnt(5)
	v_mfma_f32_32x32x16_bf16 v[80:95], v[216:219], v[100:103], v[80:95]
	ds_read_b128 v[216:219], v150 offset:128
	s_waitcnt lgkmcnt(5)
	v_mfma_f32_32x32x16_bf16 v[64:79], v[220:223], v[100:103], v[64:79]
	ds_read_b128 v[220:223], v150 offset:8320
	s_waitcnt lgkmcnt(5)
	v_mfma_f32_32x32x16_bf16 v[80:95], v[224:227], v[104:107], v[80:95]
	ds_read_b128 v[224:227], v151 offset:128
	s_waitcnt lgkmcnt(5)
	v_mfma_f32_32x32x16_bf16 v[64:79], v[228:231], v[104:107], v[64:79]
	ds_read_b128 v[228:231], v151 offset:8320
	s_waitcnt lgkmcnt(5)
	v_mfma_f32_32x32x16_bf16 v[80:95], v[208:211], v[108:111], v[80:95]
	ds_read_b128 v[208:211], v152 offset:128
	s_waitcnt lgkmcnt(5)
	v_mfma_f32_32x32x16_bf16 v[64:79], v[212:215], v[108:111], v[64:79]
	ds_read_b128 v[212:215], v152 offset:8320
	s_waitcnt lgkmcnt(5)
	v_mfma_f32_32x32x16_bf16 v[80:95], v[216:219], v[112:115], v[80:95]
	ds_read_b128 v[216:219], v153 offset:128
	s_waitcnt lgkmcnt(5)
	v_mfma_f32_32x32x16_bf16 v[64:79], v[220:223], v[112:115], v[64:79]
	ds_read_b128 v[220:223], v153 offset:8320
	s_waitcnt lgkmcnt(5)
	v_mfma_f32_32x32x16_bf16 v[80:95], v[224:227], v[116:119], v[80:95]
	s_waitcnt lgkmcnt(4)
	v_mfma_f32_32x32x16_bf16 v[64:79], v[228:231], v[116:119], v[64:79]
	s_waitcnt lgkmcnt(3)
	v_mfma_f32_32x32x16_bf16 v[80:95], v[208:211], v[120:123], v[80:95]
	s_waitcnt lgkmcnt(2)
	v_mfma_f32_32x32x16_bf16 v[64:79], v[212:215], v[120:123], v[64:79]
	s_waitcnt lgkmcnt(1)
	v_mfma_f32_32x32x16_bf16 v[80:95], v[216:219], v[124:127], v[80:95]
	s_waitcnt lgkmcnt(0)
	v_mfma_f32_32x32x16_bf16 v[64:79], v[220:223], v[124:127], v[64:79]
	v_mov_b32_e32 v149, v132
	v_mov_b32_e32 v150, v193
	v_mov_b32_e32 v151, v133
	s_nop 0
	v_lshlrev_b32_e32 v150, 2, v150
	v_sub_u32_e32 v149, s6, v149
	v_add_u32_e32 v149, v149, v150
	v_sub_u32_e32 v154, v150, v151
	v_and_b32_e32 v162, -16, v154
	v_add_u32_e32 v153, 0xe8, v149
	v_add_u32_e32 v149, 0x108, v149
	v_cmp_eq_u32_e32 vcc, s8, v162
	v_cmp_gt_u32_e64 s[6:7], 16, v154
	v_mov_b32_e32 v150, 0xff800000
	v_cndmask_b32_e32 v149, 0, v149, vcc
	v_lshl_add_u32 v149, v149, 2, 0
	v_add_u32_e32 v149, 0x18800, v149
	ds_read_b32 v152, v149
	v_mov_b32_e32 v149, 0xff800000
	s_and_saveexec_b64 s[8:9], s[6:7]
	s_cbranch_execz .LBB0_388
	v_lshl_add_u32 v150, v153, 2, 0
	v_add_u32_e32 v150, 0x18800, v150
	ds_read_b32 v150, v150
	s_waitcnt lgkmcnt(0)
	v_add_f32_e32 v150, v80, v150

; __device__ __forceinline__ void finishSM(f32x16& p0, f32x16& p1, float alpha, float& l_reg, bf16x8& pa0, bf16x8& pa1, bf16x8& pa2, bf16x8& pa3) {
; #pragma unroll
;   for (int r = 0; r < 16; ++r) p1[r] = __builtin_amdgcn_exp2f(p1[r]);
;   float ps = 0;
; #pragma unroll
;   for (int r = 0; r < 16; ++r) ps += p0[r];
; #pragma unroll
;   for (int r = 0; r < 16; ++r) ps += p1[r];
;   { auto rr = __builtin_amdgcn_permlane32_swap(__float_as_uint(ps), __float_as_uint(ps), false, false);
;     ps = __uint_as_float(rr[0]) + __uint_as_float(rr[1]); }
;   l_reg = l_reg * alpha + ps;
;     ...
;   PK4(p0, 0, pa0); PK4(p0, 8, pa1); PK4(p1, 0, pa2); PK4(p1, 8, pa3);
; template <int D0> __device__ __forceinline__ void pv_one(f32x16& od, int vb, bf16x8 pa0, bf16x8 pa1, bf16x8 pa2, bf16x8 pa3) {
;   s16x4 l0 = tr_read<v_rd_off(D0, 0, 0)>(vb), h0 = tr_read<v_rd_off(D0, 0, 1)>(vb), l1 = tr_read<v_rd_off(D0, 1, 0)>(vb), h1 = tr_read<v_rd_off(D0, 1, 1)>(vb);
;   s16x4 l2 = tr_read<v_rd_off(D0, 2, 0)>(vb), h2 = tr_read<v_rd_off(D0, 2, 1)>(vb), l3 = tr_read<v_rd_off(D0, 3, 0)>(vb), h3 = tr_read<v_rd_off(D0, 3, 1)>(vb);
;   asm volatile("s_waitcnt lgkmcnt(0)" : "+v"(l0), "+v"(h0), "+v"(l1), "+v"(h1), "+v"(l2), "+v"(h2), "+v"(l3), "+v"(h3) :: "memory");
;     ...
;   od = __builtin_amdgcn_mfma_f32_32x32x16_bf16(pa0, PK(l0, h0), od, 0, 0, 0);
;   od = __builtin_amdgcn_mfma_f32_32x32x16_bf16(pa1, PK(l1, h1), od, 0, 0, 0);
;   od = __builtin_amdgcn_mfma_f32_32x32x16_bf16(pa2, PK(l2, h2), od, 0, 0, 0);
;   od = __builtin_amdgcn_mfma_f32_32x32x16_bf16(pa3, PK(l3, h3), od, 0, 0, 0);
;     ...
; }
; __device__ __forceinline__ void pv_d0(f32x16* o, int vb, bf16x8 pa0, bf16x8 pa1, bf16x8 pa2, bf16x8 pa3) {
;   pv_one<0>(o[0], vb, pa0, pa1, pa2, pa3); pv_one<1>(o[1], vb, pa0, pa1, pa2, pa3); pv_one<2>(o[2], vb, pa0, pa1, pa2, pa3); pv_one<3>(o[3], vb, pa0, pa1, pa2, pa3);
.LBB0_423:
	v_mul_f32_e32 v79, 0xbe0293ee, v147
	v_fmamk_f32 v95, v150, 0x3e0293ee, v79
	v_fmamk_f32 v149, v149, 0x3e0293ee, v79
	v_fmamk_f32 v150, v151, 0x3e0293ee, v79
	v_fmamk_f32 v81, v81, 0x3e0293ee, v79
	v_fmamk_f32 v83, v83, 0x3e0293ee, v79
	v_fmamk_f32 v82, v82, 0x3e0293ee, v79
	v_fmamk_f32 v85, v85, 0x3e0293ee, v79
	v_fmamk_f32 v84, v84, 0x3e0293ee, v79
	v_fmamk_f32 v87, v87, 0x3e0293ee, v79
	v_fmamk_f32 v86, v86, 0x3e0293ee, v79
	v_fmamk_f32 v89, v89, 0x3e0293ee, v79
	v_fmamk_f32 v88, v88, 0x3e0293ee, v79
	v_fmamk_f32 v91, v91, 0x3e0293ee, v79
	v_fmamk_f32 v90, v90, 0x3e0293ee, v79
	v_fmamk_f32 v93, v93, 0x3e0293ee, v79
	v_fmamk_f32 v92, v92, 0x3e0293ee, v79
	v_fmamk_f32 v94, v94, 0x3e0293ee, v79
	v_fmamk_f32 v65, v65, 0x3e0293ee, v79
	v_fmamk_f32 v66, v66, 0x3e0293ee, v79
	v_fmamk_f32 v67, v67, 0x3e0293ee, v79
	v_fmamk_f32 v68, v68, 0x3e0293ee, v79
	v_fmamk_f32 v69, v69, 0x3e0293ee, v79
	v_fmamk_f32 v70, v70, 0x3e0293ee, v79
	v_fmamk_f32 v71, v71, 0x3e0293ee, v79
	v_fmamk_f32 v72, v72, 0x3e0293ee, v79
	v_fmamk_f32 v73, v73, 0x3e0293ee, v79
	v_fmamk_f32 v74, v74, 0x3e0293ee, v79
	v_fmamk_f32 v75, v75, 0x3e0293ee, v79
	v_fmamk_f32 v76, v76, 0x3e0293ee, v79
	v_fmamk_f32 v77, v77, 0x3e0293ee, v79
	v_fmamk_f32 v78, v78, 0x3e0293ee, v79
	v_fmac_f32_e32 v79, 0x3e0293ee, v64
	v_exp_f32_e32 v95, v95
	v_exp_f32_e32 v149, v149
	v_exp_f32_e32 v162, v150
	v_exp_f32_e32 v163, v81
	v_exp_f32_e32 v164, v83
	v_exp_f32_e32 v165, v82
	v_exp_f32_e32 v166, v85
	v_exp_f32_e32 v167, v84
	v_exp_f32_e32 v168, v87
	v_exp_f32_e32 v169, v86
	v_exp_f32_e32 v170, v89
	v_exp_f32_e32 v171, v88
	v_exp_f32_e32 v172, v91
	v_exp_f32_e32 v173, v90
	v_exp_f32_e32 v174, v93
	v_exp_f32_e32 v175, v92
	v_exp_f32_e32 v94, v94
	v_exp_f32_e32 v176, v65
	v_exp_f32_e32 v177, v66
	v_exp_f32_e32 v178, v67
	v_exp_f32_e32 v179, v68
	v_exp_f32_e32 v180, v69
	v_exp_f32_e32 v181, v70
	v_exp_f32_e32 v83, v71
	v_exp_f32_e32 v84, v72
	v_exp_f32_e32 v85, v73
	v_exp_f32_e32 v86, v74
	v_exp_f32_e32 v87, v75
	v_exp_f32_e32 v88, v76
	v_exp_f32_e32 v89, v77
	v_exp_f32_e32 v81, v78
	v_exp_f32_e32 v82, v79
	v_cvt_pk_bf16_f32 v76, v95, v149
	v_cvt_pk_bf16_f32 v77, v162, v163
	v_cvt_pk_bf16_f32 v78, v164, v165
	v_cvt_pk_bf16_f32 v79, v166, v167
	v_cvt_pk_bf16_f32 v72, v168, v169
	v_cvt_pk_bf16_f32 v73, v170, v171
	v_cvt_pk_bf16_f32 v74, v172, v173
	v_cvt_pk_bf16_f32 v75, v174, v175
	v_cvt_pk_bf16_f32 v68, v94, v176
	v_cvt_pk_bf16_f32 v69, v177, v178
	v_cvt_pk_bf16_f32 v70, v179, v180
	v_cvt_pk_bf16_f32 v71, v181, v83
	v_cvt_pk_bf16_f32 v64, v84, v85
	v_cvt_pk_bf16_f32 v65, v86, v87
	v_cvt_pk_bf16_f32 v66, v88, v89
	v_cvt_pk_bf16_f32 v67, v81, v82
	v_add_u32_e32 v182, s90, v146
	ds_read_b64_tr_b16 v[90:91], v182 offset:0
	ds_read_b64_tr_b16 v[92:93], v182 offset:0x800
	ds_read_b64_tr_b16 v[150:151], v182 offset:0x1000
	v_permlane32_swap_b32_e32 v76, v78
	v_permlane32_swap_b32_e32 v77, v79
	ds_read_b64_tr_b16 v[152:153], v182 offset:0x1800
	ds_read_b64_tr_b16 v[154:155], v182 offset:0x2000
	ds_read_b64_tr_b16 v[156:157], v182 offset:0x2800
	ds_read_b64_tr_b16 v[158:159], v182 offset:0x3000
	ds_read_b64_tr_b16 v[160:161], v182 offset:0x3800
	v_permlane32_swap_b32_e32 v72, v74
	s_waitcnt lgkmcnt(0)
	v_permlane32_swap_b32_e32 v73, v75
	v_mfma_f32_32x32x16_bf16 v[0:15], v[76:79], v[90:93], v[0:15]
	v_permlane32_swap_b32_e32 v68, v70
	v_permlane32_swap_b32_e32 v69, v71
	ds_read_b64_tr_b16 v[90:91], v182 offset:0x200
	v_permlane32_swap_b32_e32 v64, v66
	v_mfma_f32_32x32x16_bf16 v[0:15], v[72:75], v[150:153], v[0:15]
	v_permlane32_swap_b32_e32 v65, v67
	ds_read_b64_tr_b16 v[92:93], v182 offset:0xa00
	ds_read_b64_tr_b16 v[150:151], v182 offset:0x1200
	ds_read_b64_tr_b16 v[152:153], v182 offset:0x1a00
	v_mfma_f32_32x32x16_bf16 v[0:15], v[68:71], v[154:157], v[0:15]
	ds_read_b64_tr_b16 v[154:155], v182 offset:0x2200
	ds_read_b64_tr_b16 v[156:157], v182 offset:0x2a00
	s_nop 0
	v_mfma_f32_32x32x16_bf16 v[0:15], v[64:67], v[158:161], v[0:15]
	ds_read_b64_tr_b16 v[158:159], v182 offset:0x3200
	ds_read_b64_tr_b16 v[160:161], v182 offset:0x3a00
	s_nop 0
	s_waitcnt lgkmcnt(0)
	s_nop 0
	v_mfma_f32_32x32x16_bf16 v[48:63], v[76:79], v[90:93], v[48:63]
	ds_read_b64_tr_b16 v[90:91], v182 offset:0x400
	ds_read_b64_tr_b16 v[92:93], v182 offset:0xc00
	v_mfma_f32_32x32x16_bf16 v[48:63], v[72:75], v[150:153], v[48:63]
	ds_read_b64_tr_b16 v[150:151], v182 offset:0x1400
	ds_read_b64_tr_b16 v[152:153], v182 offset:0x1c00
	v_mfma_f32_32x32x16_bf16 v[48:63], v[68:71], v[154:157], v[48:63]
	ds_read_b64_tr_b16 v[154:155], v182 offset:0x2400
	ds_read_b64_tr_b16 v[156:157], v182 offset:0x2c00
	v_mfma_f32_32x32x16_bf16 v[48:63], v[64:67], v[158:161], v[48:63]
	ds_read_b64_tr_b16 v[158:159], v182 offset:0x3400
	ds_read_b64_tr_b16 v[160:161], v182 offset:0x3c00
	s_nop 0
	s_waitcnt lgkmcnt(0)
	s_nop 0
	v_mfma_f32_32x32x16_bf16 v[32:47], v[76:79], v[90:93], v[32:47]
	v_add_f32_e32 v90, 0, v95
	v_add_f32_e32 v90, v149, v90
	v_add_f32_e32 v90, v162, v90
	v_add_f32_e32 v90, v163, v90
	v_add_f32_e32 v90, v164, v90
	v_add_f32_e32 v90, v165, v90
	v_add_f32_e32 v90, v166, v90
	v_mfma_f32_32x32x16_bf16 v[32:47], v[72:75], v[150:153], v[32:47]
	v_add_f32_e32 v90, v167, v90
	v_add_f32_e32 v90, v168, v90
	v_add_f32_e32 v90, v169, v90
	v_add_f32_e32 v90, v170, v90
	v_add_f32_e32 v90, v171, v90
	v_add_f32_e32 v90, v172, v90
	v_add_f32_e32 v90, v173, v90
	v_mfma_f32_32x32x16_bf16 v[32:47], v[68:71], v[154:157], v[32:47]
	v_add_f32_e32 v90, v174, v90
	v_add_f32_e32 v95, v175, v90
	ds_read_b64_tr_b16 v[90:91], v182 offset:0x600
	ds_read_b64_tr_b16 v[92:93], v182 offset:0xe00
	ds_read_b64_tr_b16 v[150:151], v182 offset:0x1600
	ds_read_b64_tr_b16 v[152:153], v182 offset:0x1e00
	ds_read_b64_tr_b16 v[154:155], v182 offset:0x2600
	ds_read_b64_tr_b16 v[156:157], v182 offset:0x2e00
	v_mfma_f32_32x32x16_bf16 v[32:47], v[64:67], v[158:161], v[32:47]
	ds_read_b64_tr_b16 v[158:159], v182 offset:0x3600
	ds_read_b64_tr_b16 v[160:161], v182 offset:0x3e00
	s_nop 0
	s_waitcnt lgkmcnt(0)
	s_nop 0
	v_mfma_f32_32x32x16_bf16 v[16:31], v[76:79], v[90:93], v[16:31]
	v_add_f32_e32 v76, v94, v95
	v_add_f32_e32 v76, v176, v76
	v_add_f32_e32 v76, v177, v76
	v_add_f32_e32 v76, v178, v76
	v_add_f32_e32 v76, v179, v76
	v_add_f32_e32 v76, v180, v76
	v_add_f32_e32 v76, v181, v76
	v_mfma_f32_32x32x16_bf16 v[16:31], v[72:75], v[150:153], v[16:31]
	v_add_f32_e32 v72, v83, v76
	v_add_f32_e32 v72, v84, v72
	v_add_f32_e32 v72, v85, v72
	v_add_f32_e32 v72, v86, v72
	v_add_f32_e32 v72, v87, v72
	v_add_f32_e32 v72, v88, v72
	v_add_f32_e32 v72, v89, v72
	v_mfma_f32_32x32x16_bf16 v[16:31], v[68:71], v[154:157], v[16:31]
	v_add_f32_e32 v68, v81, v72
	v_add_f32_e32 v68, v82, v68
	v_mov_b32_e32 v69, v68
	s_nop 1
	v_permlane32_swap_b32_e32 v68, v69
	v_add_f32_e32 v68, v68, v69
	v_fmac_f32_e32 v68, v148, v80
	v_mfma_f32_32x32x16_bf16 v[16:31], v[64:67], v[158:161], v[16:31]
	v_mov_b32_e32 v148, v68
.LBB0_424:
	s_cmp_eq_u32 s58, s83
	s_cbranch_scc1 .LBB0_427
	s_mov_b32 s16, s58
	s_add_i32 s98, s98, 1
	s_cmp_eq_u32 s98, 3
	s_cselect_b32 s98, 0, s98
	s_branch .LBB0_379

; #define DMA_TILE(T) do { const AGAS char* kb_ = (const AGAS char*)Kh + (size_t)(T) * (KVBLK * LDK * 2); const AGAS char* v0_ = (const AGAS char*)V0h + (size_t)(T) * (KVBLK * LDK * 2); \
;     const AGAS char* v1_ = (const AGAS char*)V1h + (size_t)(T) * (KVBLK * LDK * 2); _Pragma("unroll") for (int i_ = 0; i_ < 6; ++i_) dma_piece(kb_, v0_, v1_, lds, (T) & 1, wid * 6 + i_, lane); } while (0)
; __device__ __forceinline__ void attn_body3n(const AGAS bf16* __restrict__ Qb, const AGAS bf16* __restrict__ Kh, const AGAS bf16* __restrict__ V0h, AGAS bf16* __restrict__ Ob, int ldo, int NT, Mod M, ALAS char* lds) {
;     ...
;   asm volatile("s_waitcnt vmcnt(0) lgkmcnt(0)" ::: "memory"); __builtin_amdgcn_s_barrier();
;   DMA_TILE(0);
;   for (int j = 0; j < NT; ++j) {
;     asm volatile("s_waitcnt vmcnt(0) lgkmcnt(0)" ::: "memory");
;     __builtin_amdgcn_s_barrier(); asm volatile("" ::: "memory");
;     if (j + 1 < NT) DMA_TILE(j + 1);
; template <int ch>
; __device__ __forceinline__ void chunk_body(const Args& a, LAS unsigned char* lds, const XcdBarrier& bar, const int G, const int bx, const int vcu, const int gw, const int NGW, const int tid, const int lane, const int wave) {
;     ...
;                 const int r0 = qb * 4; int kr0 = r0 - 4; kr0 = kr0 < 0 ? 0 : (kr0 > R - 8 ? R - 8 : kr0);
;                 const int NT = (R - kr0) < 12 ? (R - kr0) : 12;
;                 __syncthreads();
;                 for (int i = tid; i < 465; i += NWAVES * 64) tab[i] = ((const GAS float*)a.rpb)[h * 465 + i] * (1.0f / att::SCALE);
;                 const GAS bf16* Q = (const GAS bf16*)SEG + ((size_t)(24 + h) * TC + tok0 + qb * 256) * 128;
;                 const GAS bf16* K = (const GAS bf16*)SEG + ((size_t)(32 + h) * TC + tok0 + kr0 * 64) * 128;
;                 const GAS bf16* V = (const GAS bf16*)SEG + ((size_t)(40 + h) * TC + tok0 + kr0 * 64) * 128;
;                 GAS bf16* O = (GAS bf16*)ON + (tok0 + qb * 256) * DM + h * 128;
;                 att::Mod M; M.a0 = 0.f; M.a1 = 0.f; M.jd = 0; M.cen = 0; M.rq = r0 + (wave >> 1); { int t = M.rq - 4; M.rsq = t < 0 ? 0 : (t > R - 8 ? R - 8 : t); }
;                 M.kr0 = kr0; M.c = (wave & 1) * 32 + r32; { int t = M.c - 8; M.cs = t < 0 ? 0 : (t > 48 ? 48 : t); } M.hi = hi; M.tab = tab;
;                 M.tab = (const LAS float*)(lds + att::B3_WS + 2048);
;                 att::attn_body3n(Q, K, V, O, DM, NT, M, (LAS char*)lds);
.LBB0_1034:
	s_min_u32 s83, s14, 11
	s_cmp_eq_u32 s86, 0
	s_cselect_b32 s83, 8, s83
	s_and_b32 s14, s18, 0x3fffffc0
	s_lshl_b32 s14, s14, 2
	s_add_i32 s82, s14, 0
	s_add_i32 s86, s86, s72
	s_add_i32 s82, s82, 0x18000
	s_add_u32 s80, s53, s8
	s_addc_u32 s81, s55, s9
	s_lshl_b32 s8, s13, 10
	s_add_i32 m0, s22, s8
	v_lshlrev_b32_e32 v13, 4, v2
	global_load_lds_dwordx4 v19, s[80:81]
	s_lshl_b32 s13, s19, 2
	v_lshlrev_b32_e32 v17, 1, v2
	v_and_b32_e32 v13, 0xc0, v13
	v_and_b32_e32 v3, 0x100, v3
	v_cmp_gt_u32_e64 s[8:9], 32, v2
	v_or3_b32 v2, s13, v5, v1
	v_lshl_or_b32 v5, v6, 4, v7
	v_and_or_b32 v6, v8, 51, v1
	v_and_or_b32 v1, v14, 51, v1
	v_med3_i32 v12, s86, 4, 28
	v_and_b32_e32 v17, 32, v17
	v_lshl_or_b32 v2, v2, 8, v4
	v_lshlrev_b32_e32 v1, 8, v1
	v_lshl_or_b32 v145, v15, 4, v16
	v_or3_b32 v0, v13, v3, v0
	v_mov_b32_e32 v14, v129
	v_mov_b32_e32 v15, v129
	v_add_u32_e32 v139, -4, v12
	v_add_u32_e32 v141, 4, v12
	v_lshl_or_b32 v142, v6, 8, v9
	v_lshl_or_b32 v143, v10, 4, v11
	v_or3_b32 v144, v1, v4, s11
	v_cndmask_b32_e64 v128, v2, v5, s[0:1]
	v_add3_u32 v146, v17, 0, v0
	v_mov_b32_e32 v0, v129
	v_mov_b32_e32 v1, v129
	v_mov_b32_e32 v2, v129
	v_mov_b32_e32 v3, v129
	v_mov_b32_e32 v4, v129
	v_mov_b32_e32 v5, v129
	v_mov_b32_e32 v6, v129
	v_mov_b32_e32 v7, v129
	v_mov_b32_e32 v8, v129
	v_mov_b32_e32 v9, v129
	v_mov_b32_e32 v10, v129
	v_mov_b32_e32 v11, v129
	v_mov_b32_e32 v12, v129
	v_mov_b32_e32 v13, v129
	v_mov_b64_e32 v[62:63], v[14:15]
	v_mov_b64_e32 v[46:47], v[14:15]
	v_mov_b64_e32 v[30:31], v[14:15]
	v_lshl_add_u32 v140, v136, 2, s82
	s_lshl_b32 s87, s12, 10
	s_mov_b32 s20, 0
	v_mov_b32_e32 v148, 0
	v_mov_b32_e32 v147, 0xf149f2ca
	v_mov_b64_e32 v[60:61], v[12:13]
	v_mov_b64_e32 v[58:59], v[10:11]
	v_mov_b64_e32 v[56:57], v[8:9]
	v_mov_b64_e32 v[54:55], v[6:7]
	v_mov_b64_e32 v[52:53], v[4:5]
	v_mov_b64_e32 v[50:51], v[2:3]
	v_mov_b64_e32 v[48:49], v[0:1]
	v_mov_b64_e32 v[44:45], v[12:13]
	v_mov_b64_e32 v[42:43], v[10:11]
	v_mov_b64_e32 v[40:41], v[8:9]
	v_mov_b64_e32 v[38:39], v[6:7]
	v_mov_b64_e32 v[36:37], v[4:5]
	v_mov_b64_e32 v[34:35], v[2:3]
	v_mov_b64_e32 v[32:33], v[0:1]
	v_mov_b64_e32 v[28:29], v[12:13]
	v_mov_b64_e32 v[26:27], v[10:11]
	v_mov_b64_e32 v[24:25], v[8:9]
	v_mov_b64_e32 v[22:23], v[6:7]
	v_mov_b64_e32 v[20:21], v[4:5]
	v_mov_b64_e32 v[18:19], v[2:3]
	v_mov_b64_e32 v[16:17], v[0:1]
	s_waitcnt vmcnt(0)
	s_mov_b32 s98, 0
.LBB0_1035:
	s_add_i32 s48, s20, 1
	s_cmp_ge_u32 s48, s83
	s_cbranch_scc1 .Lna_w0_1
	s_waitcnt vmcnt(4) lgkmcnt(0)
	s_branch .Lna_w1_1

; #define ALAS __attribute__((address_space(3)))
; #define AGAS __attribute__((address_space(1)))
; #define DMA_TILE(T) do { const AGAS char* kb_ = (const AGAS char*)Kh + (size_t)(T) * (KVBLK * LDK * 2); const AGAS char* v0_ = (const AGAS char*)V0h + (size_t)(T) * (KVBLK * LDK * 2); \
;     const AGAS char* v1_ = (const AGAS char*)V1h + (size_t)(T) * (KVBLK * LDK * 2); _Pragma("unroll") for (int i_ = 0; i_ < 6; ++i_) dma_piece(kb_, v0_, v1_, lds, (T) & 1, wid * 6 + i_, lane); } while (0)
; #define DMA_TILE(T) do { const AGAS char* kb_ = (const AGAS char*)Kh + (size_t)(T) * (KVBLK * LDK * 2); const AGAS char* v0_ = (const AGAS char*)V0h + (size_t)(T) * (KVBLK * LDK * 2); \
;     _Pragma("unroll") for (int i_ = 0; i_ < 4; ++i_) dma_piece(kb_, v0_, v0_, lds, (T) & 1, wid * 4 + i_, lane); } while (0)
; __device__ __forceinline__ void dma_piece(const AGAS char* Kb, const AGAS char* V0b, const AGAS char* V1b, ALAS char* lds, int buf, int pc, int lane) {
;   const int img = pc >> 4, pp = pc & 15, q = pp * 64 + lane;
;   unsigned goff; const AGAS char* gb; ALAS char* dst;
;   if (img == 0) { const int row = q >> 4, ch = (q & 15) ^ (row & 7); goff = (unsigned)(row * (LDK * 2) + ch * 16); gb = Kb; dst = lds + B3_K + buf * 16384 + pp * 1024; }
;   else { const int sub = q >> 5, within = q & 31, kk = (sub >> 2) * 8 + (within >> 2), k = (kk & ~0xC) | ((kk & 4) << 1) | ((kk & 8) >> 1), c = (sub & 3) * 32 + (within & 3) * 8;
;          goff = (unsigned)(k * (LDK * 2) + c * 2); gb = img == 1 ? V0b : V1b; dst = lds + B3_V + buf * 32768 + (img - 1) * 16384 + pp * 1024; }
;   __builtin_amdgcn_global_load_lds((const AGAS unsigned*)(gb + goff), (ALAS unsigned*)dst, 16, 0, 0);
; __device__ __forceinline__ void attn_body3n(const AGAS bf16* __restrict__ Qb, const AGAS bf16* __restrict__ Kh, const AGAS bf16* __restrict__ V0h, AGAS bf16* __restrict__ Ob, int ldo, int NT, Mod M, ALAS char* lds) {
;     ...
;   asm volatile("s_waitcnt vmcnt(0) lgkmcnt(0)" ::: "memory"); __builtin_amdgcn_s_barrier();
;   DMA_TILE(0);
;   for (int j = 0; j < NT; ++j) {
;     asm volatile("s_waitcnt vmcnt(0) lgkmcnt(0)" ::: "memory");
;     __builtin_amdgcn_s_barrier(); asm volatile("" ::: "memory");
;     if (j + 1 < NT) DMA_TILE(j + 1);
.Lna_w1_1:
	s_barrier
	s_add_i32 s100, s20, 2
	s_mov_b32 s101, 0
	s_cmp_eq_u32 s20, 0
	s_cbranch_scc0 .Lna_blk_1
	s_mov_b32 s100, 1
.Lna_blk_1:
	s_cmp_ge_u32 s100, s83
	s_cbranch_scc1 .LBB0_1041
	s_mul_i32 s99, s100, 11
	s_lshr_b32 s99, s99, 5
	s_mul_i32 s99, s99, 3
	s_sub_i32 s99, s100, s99
	s_lshl_b32 s13, s99, 15
	s_lshl_b32 s12, s99, 14
	s_cmp_eq_u32 s99, 2
	s_cselect_b32 s13, 0xc000, s13
	s_cselect_b32 s12, 0xffff4000, s12
	s_add_i32 s13, s44, s13
	s_add_i32 s22, s12, 0
	s_lshl_b64 s[14:15], s[100:101], 14
	s_add_i32 s21, s13, 0xffffc000
	s_add_i32 s22, s22, 0x10000
	s_and_b64 s[12:13], s[0:1], exec
	s_cselect_b32 s23, s22, s21
	s_add_u32 s16, s80, s14
	s_addc_u32 s17, s81, s15
	s_add_i32 m0, s23, s87
	v_lshl_add_u64 v[64:65], s[16:17], 0, v[128:129]
	global_load_lds_dwordx4 v[64:65], off
	v_cndmask_b32_e64 v64, 0, 1, s[0:1]
	v_cmp_ne_u32_e64 s[12:13], 1, v64
	s_andn2_b64 vcc, exec, s[0:1]
	v_mov_b32_e32 v64, v144
	s_mov_b32 s24, s56
	s_mov_b32 s25, s52
	s_mov_b32 s26, s21
	s_mov_b64 s[18:19], s[78:79]
	v_mov_b32_e32 v65, v142
	s_cbranch_vccnz .LBB0_1038
	v_mov_b32_e32 v64, v145
	s_mov_b32 s24, s54
	s_mov_b32 s25, s45
	s_mov_b32 s26, s22
	s_mov_b64 s[18:19], s[76:77]
	v_mov_b32_e32 v65, v143

; #define ALAS __attribute__((address_space(3)))
; __device__ __forceinline__ void qkt(f32x16& p0, f32x16& p1, const ALAS char* Ks, const bf16x8* qr, int r32, int hi) {
;   p0 = f32x16{}; p1 = f32x16{};
; #pragma unroll
;   for (int d0 = 0; d0 < 8; ++d0) { int cb = (d0 * 16 + hi * 8) * 2;
;     bf16x8 b0 = *(const ALAS bf16x8*)(Ks + KSWZ(r32, cb));
;     bf16x8 b1 = *(const ALAS bf16x8*)(Ks + KSWZ(32 + r32, cb));
;     p0 = __builtin_amdgcn_mfma_f32_32x32x16_bf16(b0, qr[d0], p0, 0, 0, 0);
;     p1 = __builtin_amdgcn_mfma_f32_32x32x16_bf16(b1, qr[d0], p1, 0, 0, 0); }
; }
; __device__ __forceinline__ void attn_body3n(const AGAS bf16* __restrict__ Qb, const AGAS bf16* __restrict__ Kh, const AGAS bf16* __restrict__ V0h, AGAS bf16* __restrict__ Ob, int ldo, int NT, Mod M, ALAS char* lds) {
;     ...
;     { const int kr = M.kr0 + j; if (!(kr >= M.rsq && kr < M.rsq + 8)) continue; }
;     f32x16 p0, p1; bf16x8 pa0, pa1, pa2, pa3;
;     { int r32m = r32, him = hi; asm volatile("" : "+v"(r32m), "+v"(him)); qkt(p0, p1, lds + B3_K + (j & 1) * 16384, qr, r32m, him); }
;     float mn, alpha, bo0; { Mod Mv = M; asm volatile("" : "+v"(Mv.c), "+v"(Mv.cs), "+v"(Mv.hi)); modify<1>(p0, p1, Mv, j, bo0); }
.LBB0_1040:
	s_add_u32 s12, s53, s12
	s_addc_u32 s13, s55, s13
	s_add_u32 s12, s12, s14
	s_addc_u32 s13, s13, s15
	s_lshl_b32 s14, s16, 10
	s_add_i32 m0, s21, s14
	s_nop 0
	global_load_lds_dwordx4 v64, s[12:13]
	s_cmp_eq_u32 s20, 0
	s_cbranch_scc0 .LBB0_1041
	s_cmp_eq_u32 s100, 1
	s_cbranch_scc0 .LBB0_1041
	s_mov_b32 s100, 2
	s_branch .Lna_blk_1
.LBB0_1041:
	s_add_i32 s14, s20, s7
	v_cmp_ge_i32_e32 vcc, s14, v139
	v_cmp_lt_i32_e64 s[12:13], s14, v141
	s_and_b64 s[12:13], vcc, s[12:13]
	s_andn2_b64 vcc, exec, s[12:13]
	s_cbranch_vccnz .LBB0_1080
	s_lshl_b32 s88, s98, 15
	v_mov_b32_e32 v64, v137
	v_mov_b32_e32 v65, v136
	s_lshl_b32 s12, s98, 14
	s_cmp_eq_u32 s98, 2
	s_cselect_b32 s88, 0xc000, s88
	s_cselect_b32 s12, 0xffff4000, s12
	s_add_i32 s12, s12, 0
	s_add_i32 s12, s12, 0x10000
	v_lshlrev_b32_e32 v149, 4, v64
	v_lshlrev_b32_e32 v158, 4, v65
	v_and_b32_e32 v158, 0x70, v158
	v_lshl_add_u32 v159, v65, 8, s12
	v_xad_u32 v150, v149, v158, v159
	v_add_u32_e32 v247, 32, v149
	v_xad_u32 v151, v247, v158, v159
	v_add_u32_e32 v247, 64, v149
	v_xad_u32 v152, v247, v158, v159
	v_add_u32_e32 v247, 0x60, v149
	v_xad_u32 v153, v247, v158, v159
	s_sub_i32 s12, s14, s86
	s_mul_i32 s12, s12, 31
	s_movk_i32 s14, 0xffe0
	ds_read_b128 v[208:211], v150
	ds_read_b128 v[212:215], v150 offset:8192
	ds_read_b128 v[216:219], v151
	ds_read_b128 v[220:223], v151 offset:8192
	ds_read_b128 v[224:227], v152
	ds_read_b128 v[228:231], v152 offset:8192
	s_waitcnt lgkmcnt(5)
	v_mfma_f32_32x32x16_bf16 v[80:95], v[208:211], v[96:99], 0
	ds_read_b128 v[208:211], v153
	s_waitcnt lgkmcnt(5)
	v_mfma_f32_32x32x16_bf16 v[64:79], v[212:215], v[96:99], 0
	ds_read_b128 v[212:215], v153 offset:8192
	s_waitcnt lgkmcnt(5)
	v_mfma_f32_32x32x16_bf16 v[80:95], v[216:219], v[100:103], v[80:95]
	ds_read_b128 v[216:219], v150 offset:128
	s_waitcnt lgkmcnt(5)
	v_mfma_f32_32x32x16_bf16 v[64:79], v[220:223], v[100:103], v[64:79]
	ds_read_b128 v[220:223], v150 offset:8320
	s_waitcnt lgkmcnt(5)
	v_mfma_f32_32x32x16_bf16 v[80:95], v[224:227], v[104:107], v[80:95]
	ds_read_b128 v[224:227], v151 offset:128
	s_waitcnt lgkmcnt(5)
	v_mfma_f32_32x32x16_bf16 v[64:79], v[228:231], v[104:107], v[64:79]
	ds_read_b128 v[228:231], v151 offset:8320
	s_waitcnt lgkmcnt(5)
	v_mfma_f32_32x32x16_bf16 v[80:95], v[208:211], v[108:111], v[80:95]
	ds_read_b128 v[208:211], v152 offset:128
	s_waitcnt lgkmcnt(5)
	v_mfma_f32_32x32x16_bf16 v[64:79], v[212:215], v[108:111], v[64:79]
	ds_read_b128 v[212:215], v152 offset:8320
	s_waitcnt lgkmcnt(5)
	v_mfma_f32_32x32x16_bf16 v[80:95], v[216:219], v[112:115], v[80:95]
	ds_read_b128 v[216:219], v153 offset:128
	s_waitcnt lgkmcnt(5)
	v_mfma_f32_32x32x16_bf16 v[64:79], v[220:223], v[112:115], v[64:79]
	ds_read_b128 v[220:223], v153 offset:8320
	s_waitcnt lgkmcnt(5)
	v_mfma_f32_32x32x16_bf16 v[80:95], v[224:227], v[116:119], v[80:95]
	s_waitcnt lgkmcnt(4)
	v_mfma_f32_32x32x16_bf16 v[64:79], v[228:231], v[116:119], v[64:79]
	s_waitcnt lgkmcnt(3)
	v_mfma_f32_32x32x16_bf16 v[80:95], v[208:211], v[120:123], v[80:95]
	s_waitcnt lgkmcnt(2)
	v_mfma_f32_32x32x16_bf16 v[64:79], v[212:215], v[120:123], v[64:79]
	s_waitcnt lgkmcnt(1)
	v_mfma_f32_32x32x16_bf16 v[80:95], v[216:219], v[124:127], v[80:95]
	s_waitcnt lgkmcnt(0)
	v_mfma_f32_32x32x16_bf16 v[64:79], v[220:223], v[124:127], v[64:79]
	v_mov_b32_e32 v149, v133
	v_mov_b32_e32 v150, v132
	v_mov_b32_e32 v151, v193
	s_nop 0
	v_lshlrev_b32_e32 v151, 2, v151
	v_sub_u32_e32 v154, v151, v149
	v_sub_u32_e32 v149, s12, v150
	v_add_u32_e32 v149, v149, v151
	v_and_b32_e32 v162, -16, v154
	v_add_u32_e32 v153, 0xe8, v149
	v_add_u32_e32 v149, 0x108, v149
	v_cmp_eq_u32_e32 vcc, s14, v162
	v_cmp_gt_u32_e64 s[12:13], 16, v154
	v_cndmask_b32_e32 v149, 0, v149, vcc
	v_lshl_add_u32 v149, v149, 2, 0
	v_add_u32_e32 v149, 0x18800, v149
	ds_read_b32 v152, v149
	v_mov_b32_e32 v149, 0xff800000
	v_mov_b32_e32 v150, 0xff800000
	s_and_saveexec_b64 s[14:15], s[12:13]
	s_cbranch_execz .LBB0_1044
	v_lshl_add_u32 v150, v153, 2, 0
	v_add_u32_e32 v150, 0x18800, v150
	ds_read_b32 v150, v150
	s_waitcnt lgkmcnt(0)
	v_add_f32_e32 v150, v80, v150

; __device__ __forceinline__ void finishSM(f32x16& p0, f32x16& p1, float alpha, float& l_reg, bf16x8& pa0, bf16x8& pa1, bf16x8& pa2, bf16x8& pa3) {
; #pragma unroll
;   for (int r = 0; r < 16; ++r) p1[r] = __builtin_amdgcn_exp2f(p1[r]);
;   float ps = 0;
; #pragma unroll
;   for (int r = 0; r < 16; ++r) ps += p0[r];
; #pragma unroll
;   for (int r = 0; r < 16; ++r) ps += p1[r];
;   { auto rr = __builtin_amdgcn_permlane32_swap(__float_as_uint(ps), __float_as_uint(ps), false, false);
;     ps = __uint_as_float(rr[0]) + __uint_as_float(rr[1]); }
;   l_reg = l_reg * alpha + ps;
;     ...
;   PK4(p0, 0, pa0); PK4(p0, 8, pa1); PK4(p1, 0, pa2); PK4(p1, 8, pa3);
; template <int D0> __device__ __forceinline__ void pv_one(f32x16& od, int vb, bf16x8 pa0, bf16x8 pa1, bf16x8 pa2, bf16x8 pa3) {
;   s16x4 l0 = tr_read<v_rd_off(D0, 0, 0)>(vb), h0 = tr_read<v_rd_off(D0, 0, 1)>(vb), l1 = tr_read<v_rd_off(D0, 1, 0)>(vb), h1 = tr_read<v_rd_off(D0, 1, 1)>(vb);
;   s16x4 l2 = tr_read<v_rd_off(D0, 2, 0)>(vb), h2 = tr_read<v_rd_off(D0, 2, 1)>(vb), l3 = tr_read<v_rd_off(D0, 3, 0)>(vb), h3 = tr_read<v_rd_off(D0, 3, 1)>(vb);
;   asm volatile("s_waitcnt lgkmcnt(0)" : "+v"(l0), "+v"(h0), "+v"(l1), "+v"(h1), "+v"(l2), "+v"(h2), "+v"(l3), "+v"(h3) :: "memory");
;     ...
;   od = __builtin_amdgcn_mfma_f32_32x32x16_bf16(pa0, PK(l0, h0), od, 0, 0, 0);
;   od = __builtin_amdgcn_mfma_f32_32x32x16_bf16(pa1, PK(l1, h1), od, 0, 0, 0);
;   od = __builtin_amdgcn_mfma_f32_32x32x16_bf16(pa2, PK(l2, h2), od, 0, 0, 0);
;   od = __builtin_amdgcn_mfma_f32_32x32x16_bf16(pa3, PK(l3, h3), od, 0, 0, 0);
;     ...
; }
; __device__ __forceinline__ void pv_d0(f32x16* o, int vb, bf16x8 pa0, bf16x8 pa1, bf16x8 pa2, bf16x8 pa3) {
;   pv_one<0>(o[0], vb, pa0, pa1, pa2, pa3); pv_one<1>(o[1], vb, pa0, pa1, pa2, pa3); pv_one<2>(o[2], vb, pa0, pa1, pa2, pa3); pv_one<3>(o[3], vb, pa0, pa1, pa2, pa3);
.LBB0_1079:
	v_mul_f32_e32 v79, 0xbe0293ee, v147
	v_fmamk_f32 v95, v150, 0x3e0293ee, v79
	v_fmamk_f32 v149, v149, 0x3e0293ee, v79
	v_fmamk_f32 v150, v151, 0x3e0293ee, v79
	v_fmamk_f32 v81, v81, 0x3e0293ee, v79
	v_fmamk_f32 v83, v83, 0x3e0293ee, v79
	v_fmamk_f32 v82, v82, 0x3e0293ee, v79
	v_fmamk_f32 v85, v85, 0x3e0293ee, v79
	v_fmamk_f32 v84, v84, 0x3e0293ee, v79
	v_fmamk_f32 v87, v87, 0x3e0293ee, v79
	v_fmamk_f32 v86, v86, 0x3e0293ee, v79
	v_fmamk_f32 v89, v89, 0x3e0293ee, v79
	v_fmamk_f32 v88, v88, 0x3e0293ee, v79
	v_fmamk_f32 v91, v91, 0x3e0293ee, v79
	v_fmamk_f32 v90, v90, 0x3e0293ee, v79
	v_fmamk_f32 v93, v93, 0x3e0293ee, v79
	v_fmamk_f32 v92, v92, 0x3e0293ee, v79
	v_fmamk_f32 v94, v94, 0x3e0293ee, v79
	v_fmamk_f32 v65, v65, 0x3e0293ee, v79
	v_fmamk_f32 v66, v66, 0x3e0293ee, v79
	v_fmamk_f32 v67, v67, 0x3e0293ee, v79
	v_fmamk_f32 v68, v68, 0x3e0293ee, v79
	v_fmamk_f32 v69, v69, 0x3e0293ee, v79
	v_fmamk_f32 v70, v70, 0x3e0293ee, v79
	v_fmamk_f32 v71, v71, 0x3e0293ee, v79
	v_fmamk_f32 v72, v72, 0x3e0293ee, v79
	v_fmamk_f32 v73, v73, 0x3e0293ee, v79
	v_fmamk_f32 v74, v74, 0x3e0293ee, v79
	v_fmamk_f32 v75, v75, 0x3e0293ee, v79
	v_fmamk_f32 v76, v76, 0x3e0293ee, v79
	v_fmamk_f32 v77, v77, 0x3e0293ee, v79
	v_fmamk_f32 v78, v78, 0x3e0293ee, v79
	v_fmac_f32_e32 v79, 0x3e0293ee, v64
	v_exp_f32_e32 v95, v95
	v_exp_f32_e32 v149, v149
	v_exp_f32_e32 v162, v150
	v_exp_f32_e32 v163, v81
	v_exp_f32_e32 v164, v83
	v_exp_f32_e32 v165, v82
	v_exp_f32_e32 v166, v85
	v_exp_f32_e32 v167, v84
	v_exp_f32_e32 v168, v87
	v_exp_f32_e32 v169, v86
	v_exp_f32_e32 v170, v89
	v_exp_f32_e32 v171, v88
	v_exp_f32_e32 v172, v91
	v_exp_f32_e32 v173, v90
	v_exp_f32_e32 v174, v93
	v_exp_f32_e32 v175, v92
	v_exp_f32_e32 v94, v94
	v_exp_f32_e32 v176, v65
	v_exp_f32_e32 v177, v66
	v_exp_f32_e32 v178, v67
	v_exp_f32_e32 v179, v68
	v_exp_f32_e32 v180, v69
	v_exp_f32_e32 v181, v70
	v_exp_f32_e32 v83, v71
	v_exp_f32_e32 v84, v72
	v_exp_f32_e32 v85, v73
	v_exp_f32_e32 v86, v74
	v_exp_f32_e32 v87, v75
	v_exp_f32_e32 v88, v76
	v_exp_f32_e32 v89, v77
	v_exp_f32_e32 v81, v78
	v_exp_f32_e32 v82, v79
	v_cvt_pk_bf16_f32 v76, v95, v149
	v_cvt_pk_bf16_f32 v77, v162, v163
	v_cvt_pk_bf16_f32 v78, v164, v165
	v_cvt_pk_bf16_f32 v79, v166, v167
	v_cvt_pk_bf16_f32 v72, v168, v169
	v_cvt_pk_bf16_f32 v73, v170, v171
	v_cvt_pk_bf16_f32 v74, v172, v173
	v_cvt_pk_bf16_f32 v75, v174, v175
	v_cvt_pk_bf16_f32 v68, v94, v176
	v_cvt_pk_bf16_f32 v69, v177, v178
	v_cvt_pk_bf16_f32 v70, v179, v180
	v_cvt_pk_bf16_f32 v71, v181, v83
	v_cvt_pk_bf16_f32 v64, v84, v85
	v_cvt_pk_bf16_f32 v65, v86, v87
	v_cvt_pk_bf16_f32 v66, v88, v89
	v_cvt_pk_bf16_f32 v67, v81, v82
	v_add_u32_e32 v182, s88, v146
	ds_read_b64_tr_b16 v[90:91], v182 offset:0
	ds_read_b64_tr_b16 v[92:93], v182 offset:0x800
	ds_read_b64_tr_b16 v[150:151], v182 offset:0x1000
	v_permlane32_swap_b32_e32 v76, v78
	v_permlane32_swap_b32_e32 v77, v79
	ds_read_b64_tr_b16 v[152:153], v182 offset:0x1800
	ds_read_b64_tr_b16 v[154:155], v182 offset:0x2000
	ds_read_b64_tr_b16 v[156:157], v182 offset:0x2800
	ds_read_b64_tr_b16 v[158:159], v182 offset:0x3000
	ds_read_b64_tr_b16 v[160:161], v182 offset:0x3800
	v_permlane32_swap_b32_e32 v72, v74
	s_waitcnt lgkmcnt(0)
	v_permlane32_swap_b32_e32 v73, v75
	v_mfma_f32_32x32x16_bf16 v[0:15], v[76:79], v[90:93], v[0:15]
	v_permlane32_swap_b32_e32 v68, v70
	v_permlane32_swap_b32_e32 v69, v71
	ds_read_b64_tr_b16 v[90:91], v182 offset:0x200
	v_permlane32_swap_b32_e32 v64, v66
	v_mfma_f32_32x32x16_bf16 v[0:15], v[72:75], v[150:153], v[0:15]
	v_permlane32_swap_b32_e32 v65, v67
	ds_read_b64_tr_b16 v[92:93], v182 offset:0xa00
	ds_read_b64_tr_b16 v[150:151], v182 offset:0x1200
	ds_read_b64_tr_b16 v[152:153], v182 offset:0x1a00
	v_mfma_f32_32x32x16_bf16 v[0:15], v[68:71], v[154:157], v[0:15]
	ds_read_b64_tr_b16 v[154:155], v182 offset:0x2200
	ds_read_b64_tr_b16 v[156:157], v182 offset:0x2a00
	s_nop 0
	v_mfma_f32_32x32x16_bf16 v[0:15], v[64:67], v[158:161], v[0:15]
	ds_read_b64_tr_b16 v[158:159], v182 offset:0x3200
	ds_read_b64_tr_b16 v[160:161], v182 offset:0x3a00
	s_nop 0
	s_waitcnt lgkmcnt(0)
	s_nop 0
	v_mfma_f32_32x32x16_bf16 v[48:63], v[76:79], v[90:93], v[48:63]
	ds_read_b64_tr_b16 v[90:91], v182 offset:0x400
	ds_read_b64_tr_b16 v[92:93], v182 offset:0xc00
	v_mfma_f32_32x32x16_bf16 v[48:63], v[72:75], v[150:153], v[48:63]
	ds_read_b64_tr_b16 v[150:151], v182 offset:0x1400
	ds_read_b64_tr_b16 v[152:153], v182 offset:0x1c00
	v_mfma_f32_32x32x16_bf16 v[48:63], v[68:71], v[154:157], v[48:63]
	ds_read_b64_tr_b16 v[154:155], v182 offset:0x2400
	ds_read_b64_tr_b16 v[156:157], v182 offset:0x2c00
	v_mfma_f32_32x32x16_bf16 v[48:63], v[64:67], v[158:161], v[48:63]
	ds_read_b64_tr_b16 v[158:159], v182 offset:0x3400
	ds_read_b64_tr_b16 v[160:161], v182 offset:0x3c00
	s_nop 0
	s_waitcnt lgkmcnt(0)
	s_nop 0
	v_mfma_f32_32x32x16_bf16 v[32:47], v[76:79], v[90:93], v[32:47]
	v_add_f32_e32 v90, 0, v95
	v_add_f32_e32 v90, v149, v90
	v_add_f32_e32 v90, v162, v90
	v_add_f32_e32 v90, v163, v90
	v_add_f32_e32 v90, v164, v90
	v_add_f32_e32 v90, v165, v90
	v_add_f32_e32 v90, v166, v90
	v_mfma_f32_32x32x16_bf16 v[32:47], v[72:75], v[150:153], v[32:47]
	v_add_f32_e32 v90, v167, v90
	v_add_f32_e32 v90, v168, v90
	v_add_f32_e32 v90, v169, v90
	v_add_f32_e32 v90, v170, v90
	v_add_f32_e32 v90, v171, v90
	v_add_f32_e32 v90, v172, v90
	v_add_f32_e32 v90, v173, v90
	v_mfma_f32_32x32x16_bf16 v[32:47], v[68:71], v[154:157], v[32:47]
	v_add_f32_e32 v90, v174, v90
	v_add_f32_e32 v95, v175, v90
	ds_read_b64_tr_b16 v[90:91], v182 offset:0x600
	ds_read_b64_tr_b16 v[92:93], v182 offset:0xe00
	ds_read_b64_tr_b16 v[150:151], v182 offset:0x1600
	ds_read_b64_tr_b16 v[152:153], v182 offset:0x1e00
	ds_read_b64_tr_b16 v[154:155], v182 offset:0x2600
	ds_read_b64_tr_b16 v[156:157], v182 offset:0x2e00
	v_mfma_f32_32x32x16_bf16 v[32:47], v[64:67], v[158:161], v[32:47]
	ds_read_b64_tr_b16 v[158:159], v182 offset:0x3600
	ds_read_b64_tr_b16 v[160:161], v182 offset:0x3e00
	s_nop 0
	s_waitcnt lgkmcnt(0)
	s_nop 0
	v_mfma_f32_32x32x16_bf16 v[16:31], v[76:79], v[90:93], v[16:31]
	v_add_f32_e32 v76, v94, v95
	v_add_f32_e32 v76, v176, v76
	v_add_f32_e32 v76, v177, v76
	v_add_f32_e32 v76, v178, v76
	v_add_f32_e32 v76, v179, v76
	v_add_f32_e32 v76, v180, v76
	v_add_f32_e32 v76, v181, v76
	v_mfma_f32_32x32x16_bf16 v[16:31], v[72:75], v[150:153], v[16:31]
	v_add_f32_e32 v72, v83, v76
	v_add_f32_e32 v72, v84, v72
	v_add_f32_e32 v72, v85, v72
	v_add_f32_e32 v72, v86, v72
	v_add_f32_e32 v72, v87, v72
	v_add_f32_e32 v72, v88, v72
	v_add_f32_e32 v72, v89, v72
	v_mfma_f32_32x32x16_bf16 v[16:31], v[68:71], v[154:157], v[16:31]
	v_add_f32_e32 v68, v81, v72
	v_add_f32_e32 v68, v82, v68
	v_mov_b32_e32 v69, v68
	s_nop 1
	v_permlane32_swap_b32_e32 v68, v69
	v_add_f32_e32 v68, v68, v69
	v_fmac_f32_e32 v68, v148, v80
	v_mfma_f32_32x32x16_bf16 v[16:31], v[64:67], v[158:161], v[16:31]
	v_mov_b32_e32 v148, v68
.LBB0_1080:
	s_cmp_eq_u32 s48, s83
	s_cbranch_scc1 .LBB0_1083
	s_mov_b32 s20, s48
	s_add_i32 s98, s98, 1
	s_cmp_eq_u32 s98, 3
	s_cselect_b32 s98, 0, s98
	s_branch .LBB0_1035

; #define DMA_TILE(T) do { const AGAS char* kb_ = (const AGAS char*)Kh + (size_t)(T) * (KVBLK * LDK * 2); const AGAS char* v0_ = (const AGAS char*)V0h + (size_t)(T) * (KVBLK * LDK * 2); \
;     const AGAS char* v1_ = (const AGAS char*)V1h + (size_t)(T) * (KVBLK * LDK * 2); _Pragma("unroll") for (int i_ = 0; i_ < 6; ++i_) dma_piece(kb_, v0_, v1_, lds, (T) & 1, wid * 6 + i_, lane); } while (0)
; __device__ __forceinline__ void attn_body3n(const AGAS bf16* __restrict__ Qb, const AGAS bf16* __restrict__ Kh, const AGAS bf16* __restrict__ V0h, AGAS bf16* __restrict__ Ob, int ldo, int NT, Mod M, ALAS char* lds) {
;     ...
;   asm volatile("s_waitcnt vmcnt(0) lgkmcnt(0)" ::: "memory"); __builtin_amdgcn_s_barrier();
;   DMA_TILE(0);
;   for (int j = 0; j < NT; ++j) {
;     asm volatile("s_waitcnt vmcnt(0) lgkmcnt(0)" ::: "memory");
;     __builtin_amdgcn_s_barrier(); asm volatile("" ::: "memory");
;     if (j + 1 < NT) DMA_TILE(j + 1);
; template <int ch>
; __device__ __forceinline__ void chunk_body(const Args& a, LAS unsigned char* lds, const XcdBarrier& bar, const int G, const int bx, const int vcu, const int gw, const int NGW, const int tid, const int lane, const int wave) {
;     ...
;                 const int r0 = qb * 4; int kr0 = r0 - 4; kr0 = kr0 < 0 ? 0 : (kr0 > R - 8 ? R - 8 : kr0);
;                 const int NT = (R - kr0) < 12 ? (R - kr0) : 12;
;                 __syncthreads();
;                 for (int i = tid; i < 465; i += NWAVES * 64) tab[i] = ((const GAS float*)a.rpb)[h * 465 + i] * (1.0f / att::SCALE);
;                 const GAS bf16* Q = (const GAS bf16*)SEG + ((size_t)(24 + h) * TC + tok0 + qb * 256) * 128;
;                 const GAS bf16* K = (const GAS bf16*)SEG + ((size_t)(32 + h) * TC + tok0 + kr0 * 64) * 128;
;                 const GAS bf16* V = (const GAS bf16*)SEG + ((size_t)(40 + h) * TC + tok0 + kr0 * 64) * 128;
;                 GAS bf16* O = (GAS bf16*)ON + (tok0 + qb * 256) * DM + h * 128;
;                 att::Mod M; M.a0 = 0.f; M.a1 = 0.f; M.jd = 0; M.cen = 0; M.rq = r0 + (wave >> 1); { int t = M.rq - 4; M.rsq = t < 0 ? 0 : (t > R - 8 ? R - 8 : t); }
;                 M.kr0 = kr0; M.c = (wave & 1) * 32 + r32; { int t = M.c - 8; M.cs = t < 0 ? 0 : (t > 48 ? 48 : t); } M.hi = hi; M.tab = tab;
;                 M.tab = (const LAS float*)(lds + att::B3_WS + 2048);
;                 att::attn_body3n(Q, K, V, O, DM, NT, M, (LAS char*)lds);
.LBB0_1690:
	s_min_u32 s70, s8, 11
	s_cmp_eq_u32 s71, 0
	s_cselect_b32 s70, 8, s70
	s_and_b32 s8, s14, 0x3fffffc0
	s_lshl_b32 s8, s8, 2
	s_add_i32 s69, s8, 0
	s_add_i32 s71, s71, s75
	s_add_i32 s69, s69, 0x18000
	s_add_u32 s62, s53, s4
	s_addc_u32 s63, s55, s5
	s_lshl_b32 s4, s7, 10
	s_add_i32 m0, s18, s4
	v_lshlrev_b32_e32 v13, 4, v2
	global_load_lds_dwordx4 v19, s[62:63]
	s_lshl_b32 s7, s15, 2
	v_lshlrev_b32_e32 v17, 1, v2
	v_and_b32_e32 v13, 0xc0, v13
	v_and_b32_e32 v3, 0x100, v3
	v_cmp_gt_u32_e64 s[4:5], 32, v2
	v_or3_b32 v2, s7, v5, v1
	v_lshl_or_b32 v5, v6, 4, v7
	v_and_or_b32 v6, v8, 51, v1
	v_and_or_b32 v1, v14, 51, v1
	v_med3_i32 v12, s71, 4, 28
	v_and_b32_e32 v17, 32, v17
	v_lshl_or_b32 v2, v2, 8, v4
	v_lshlrev_b32_e32 v1, 8, v1
	v_lshl_or_b32 v145, v15, 4, v16
	v_or3_b32 v0, v13, v3, v0
	v_mov_b32_e32 v14, v129
	v_mov_b32_e32 v15, v129
	v_add_u32_e32 v139, -4, v12
	v_add_u32_e32 v141, 4, v12
	v_lshl_or_b32 v142, v6, 8, v9
	v_lshl_or_b32 v143, v10, 4, v11
	v_or3_b32 v144, v1, v4, s44
	v_cndmask_b32_e64 v128, v2, v5, s[0:1]
	v_add3_u32 v146, v17, 0, v0
	v_mov_b32_e32 v0, v129
	v_mov_b32_e32 v1, v129
	v_mov_b32_e32 v2, v129
	v_mov_b32_e32 v3, v129
	v_mov_b32_e32 v4, v129
	v_mov_b32_e32 v5, v129
	v_mov_b32_e32 v6, v129
	v_mov_b32_e32 v7, v129
	v_mov_b32_e32 v8, v129
	v_mov_b32_e32 v9, v129
	v_mov_b32_e32 v10, v129
	v_mov_b32_e32 v11, v129
	v_mov_b32_e32 v12, v129
	v_mov_b32_e32 v13, v129
	v_mov_b64_e32 v[62:63], v[14:15]
	v_mov_b64_e32 v[46:47], v[14:15]
	v_mov_b64_e32 v[30:31], v[14:15]
	v_lshl_add_u32 v140, v136, 2, s69
	s_lshl_b32 s72, s6, 10
	s_mov_b32 s16, 0
	v_mov_b32_e32 v147, 0
	v_mov_b32_e32 v148, 0xf149f2ca
	v_mov_b64_e32 v[60:61], v[12:13]
	v_mov_b64_e32 v[58:59], v[10:11]
	v_mov_b64_e32 v[56:57], v[8:9]
	v_mov_b64_e32 v[54:55], v[6:7]
	v_mov_b64_e32 v[52:53], v[4:5]
	v_mov_b64_e32 v[50:51], v[2:3]
	v_mov_b64_e32 v[48:49], v[0:1]
	v_mov_b64_e32 v[44:45], v[12:13]
	v_mov_b64_e32 v[42:43], v[10:11]
	v_mov_b64_e32 v[40:41], v[8:9]
	v_mov_b64_e32 v[38:39], v[6:7]
	v_mov_b64_e32 v[36:37], v[4:5]
	v_mov_b64_e32 v[34:35], v[2:3]
	v_mov_b64_e32 v[32:33], v[0:1]
	v_mov_b64_e32 v[28:29], v[12:13]
	v_mov_b64_e32 v[26:27], v[10:11]
	v_mov_b64_e32 v[24:25], v[8:9]
	v_mov_b64_e32 v[22:23], v[6:7]
	v_mov_b64_e32 v[20:21], v[4:5]
	v_mov_b64_e32 v[18:19], v[2:3]
	v_mov_b64_e32 v[16:17], v[0:1]
	s_waitcnt vmcnt(0)
	s_mov_b32 s98, 0
.LBB0_1691:
	s_add_i32 s42, s16, 1
	s_cmp_ge_u32 s42, s70
	s_cbranch_scc1 .Lna_w0_2
	s_waitcnt vmcnt(4) lgkmcnt(0)
	s_branch .Lna_w1_2

; #define ALAS __attribute__((address_space(3)))
; #define AGAS __attribute__((address_space(1)))
; __device__ __forceinline__ void dma_piece(const AGAS char* Kb, const AGAS char* V0b, const AGAS char* V1b, ALAS char* lds, int buf, int pc, int lane) {
;   const int img = pc >> 4, pp = pc & 15, q = pp * 64 + lane;
;   unsigned goff; const AGAS char* gb; ALAS char* dst;
;   if (img == 0) { const int row = q >> 4, ch = (q & 15) ^ (row & 7); goff = (unsigned)(row * (LDK * 2) + ch * 16); gb = Kb; dst = lds + B3_K + buf * 16384 + pp * 1024; }
;   else { const int sub = q >> 5, within = q & 31, kk = (sub >> 2) * 8 + (within >> 2), k = (kk & ~0xC) | ((kk & 4) << 1) | ((kk & 8) >> 1), c = (sub & 3) * 32 + (within & 3) * 8;
;          goff = (unsigned)(k * (LDK * 2) + c * 2); gb = img == 1 ? V0b : V1b; dst = lds + B3_V + buf * 32768 + (img - 1) * 16384 + pp * 1024; }
;   __builtin_amdgcn_global_load_lds((const AGAS unsigned*)(gb + goff), (ALAS unsigned*)dst, 16, 0, 0);
.Lna_blk_2:
	s_cmp_ge_u32 s100, s70
	s_cbranch_scc1 .LBB0_1697
	s_mul_i32 s99, s100, 11
	s_lshr_b32 s99, s99, 5
	s_mul_i32 s99, s99, 3
	s_sub_i32 s99, s100, s99
	s_lshl_b32 s7, s99, 15
	s_lshl_b32 s6, s99, 14
	s_cmp_eq_u32 s99, 2
	s_cselect_b32 s7, 0xc000, s7
	s_cselect_b32 s6, 0xffff4000, s6
	s_add_i32 s7, s52, s7
	s_add_i32 s18, s6, 0
	s_lshl_b64 s[8:9], s[100:101], 14
	s_add_i32 s17, s7, 0xffffc000
	s_add_i32 s18, s18, 0x10000
	s_and_b64 s[6:7], s[0:1], exec
	s_cselect_b32 s19, s18, s17
	s_add_u32 s12, s62, s8
	s_addc_u32 s13, s63, s9
	s_add_i32 m0, s19, s72
	v_lshl_add_u64 v[64:65], s[12:13], 0, v[128:129]
	global_load_lds_dwordx4 v[64:65], off
	v_cndmask_b32_e64 v64, 0, 1, s[0:1]
	v_cmp_ne_u32_e64 s[6:7], 1, v64
	s_andn2_b64 vcc, exec, s[0:1]
	v_mov_b32_e32 v64, v144
	s_mov_b32 s20, s66
	s_mov_b32 s21, s56
	s_mov_b32 s22, s17
	s_mov_b64 s[14:15], s[60:61]
	v_mov_b32_e32 v65, v142
	s_cbranch_vccnz .LBB0_1694
	v_mov_b32_e32 v64, v145
	s_mov_b32 s20, s57
	s_mov_b32 s21, s54
	s_mov_b32 s22, s18
	s_mov_b64 s[14:15], s[58:59]
	v_mov_b32_e32 v65, v143

; #define ALAS __attribute__((address_space(3)))
; __device__ __forceinline__ void qkt(f32x16& p0, f32x16& p1, const ALAS char* Ks, const bf16x8* qr, int r32, int hi) {
;   p0 = f32x16{}; p1 = f32x16{};
; #pragma unroll
;   for (int d0 = 0; d0 < 8; ++d0) { int cb = (d0 * 16 + hi * 8) * 2;
;     bf16x8 b0 = *(const ALAS bf16x8*)(Ks + KSWZ(r32, cb));
;     bf16x8 b1 = *(const ALAS bf16x8*)(Ks + KSWZ(32 + r32, cb));
;     p0 = __builtin_amdgcn_mfma_f32_32x32x16_bf16(b0, qr[d0], p0, 0, 0, 0);
;     p1 = __builtin_amdgcn_mfma_f32_32x32x16_bf16(b1, qr[d0], p1, 0, 0, 0); }
; }
; __device__ __forceinline__ void attn_body3n(const AGAS bf16* __restrict__ Qb, const AGAS bf16* __restrict__ Kh, const AGAS bf16* __restrict__ V0h, AGAS bf16* __restrict__ Ob, int ldo, int NT, Mod M, ALAS char* lds) {
;     ...
;     { const int kr = M.kr0 + j; if (!(kr >= M.rsq && kr < M.rsq + 8)) continue; }
;     f32x16 p0, p1; bf16x8 pa0, pa1, pa2, pa3;
;     { int r32m = r32, him = hi; asm volatile("" : "+v"(r32m), "+v"(him)); qkt(p0, p1, lds + B3_K + (j & 1) * 16384, qr, r32m, him); }
;     float mn, alpha, bo0; { Mod Mv = M; asm volatile("" : "+v"(Mv.c), "+v"(Mv.cs), "+v"(Mv.hi)); modify<1>(p0, p1, Mv, j, bo0); }
.LBB0_1697:
	s_add_i32 s8, s16, s47
	v_cmp_ge_i32_e32 vcc, s8, v139
	v_cmp_lt_i32_e64 s[6:7], s8, v141
	s_and_b64 s[6:7], vcc, s[6:7]
	s_andn2_b64 vcc, exec, s[6:7]
	s_cbranch_vccnz .LBB0_1736
	s_lshl_b32 s73, s98, 15
	v_mov_b32_e32 v64, v136
	v_mov_b32_e32 v65, v137
	s_lshl_b32 s6, s98, 14
	s_cmp_eq_u32 s98, 2
	s_cselect_b32 s73, 0xc000, s73
	s_cselect_b32 s6, 0xffff4000, s6
	s_add_i32 s6, s6, 0
	s_add_i32 s6, s6, 0x10000
	v_lshlrev_b32_e32 v149, 4, v65
	v_lshlrev_b32_e32 v158, 4, v64
	v_and_b32_e32 v158, 0x70, v158
	v_lshl_add_u32 v159, v64, 8, s6
	v_xad_u32 v150, v149, v158, v159
	v_add_u32_e32 v247, 32, v149
	v_xad_u32 v151, v247, v158, v159
	v_add_u32_e32 v247, 64, v149
	v_xad_u32 v152, v247, v158, v159
	v_add_u32_e32 v247, 0x60, v149
	v_xad_u32 v153, v247, v158, v159
	s_sub_i32 s6, s8, s71
	s_mul_i32 s6, s6, 31
	s_movk_i32 s8, 0xffe0
	ds_read_b128 v[208:211], v150
	ds_read_b128 v[212:215], v150 offset:8192
	ds_read_b128 v[216:219], v151
	ds_read_b128 v[220:223], v151 offset:8192
	ds_read_b128 v[224:227], v152
	ds_read_b128 v[228:231], v152 offset:8192
	s_waitcnt lgkmcnt(5)
	v_mfma_f32_32x32x16_bf16 v[80:95], v[208:211], v[96:99], 0
	ds_read_b128 v[208:211], v153
	s_waitcnt lgkmcnt(5)
	v_mfma_f32_32x32x16_bf16 v[64:79], v[212:215], v[96:99], 0
	ds_read_b128 v[212:215], v153 offset:8192
	s_waitcnt lgkmcnt(5)
	v_mfma_f32_32x32x16_bf16 v[80:95], v[216:219], v[100:103], v[80:95]
	ds_read_b128 v[216:219], v150 offset:128
	s_waitcnt lgkmcnt(5)
	v_mfma_f32_32x32x16_bf16 v[64:79], v[220:223], v[100:103], v[64:79]
	ds_read_b128 v[220:223], v150 offset:8320
	s_waitcnt lgkmcnt(5)
	v_mfma_f32_32x32x16_bf16 v[80:95], v[224:227], v[104:107], v[80:95]
	ds_read_b128 v[224:227], v151 offset:128
	s_waitcnt lgkmcnt(5)
	v_mfma_f32_32x32x16_bf16 v[64:79], v[228:231], v[104:107], v[64:79]
	ds_read_b128 v[228:231], v151 offset:8320
	s_waitcnt lgkmcnt(5)
	v_mfma_f32_32x32x16_bf16 v[80:95], v[208:211], v[108:111], v[80:95]
	ds_read_b128 v[208:211], v152 offset:128
	s_waitcnt lgkmcnt(5)
	v_mfma_f32_32x32x16_bf16 v[64:79], v[212:215], v[108:111], v[64:79]
	ds_read_b128 v[212:215], v152 offset:8320
	s_waitcnt lgkmcnt(5)
	v_mfma_f32_32x32x16_bf16 v[80:95], v[216:219], v[112:115], v[80:95]
	ds_read_b128 v[216:219], v153 offset:128
	s_waitcnt lgkmcnt(5)
	v_mfma_f32_32x32x16_bf16 v[64:79], v[220:223], v[112:115], v[64:79]
	ds_read_b128 v[220:223], v153 offset:8320
	s_waitcnt lgkmcnt(5)
	v_mfma_f32_32x32x16_bf16 v[80:95], v[224:227], v[116:119], v[80:95]
	s_waitcnt lgkmcnt(4)
	v_mfma_f32_32x32x16_bf16 v[64:79], v[228:231], v[116:119], v[64:79]
	s_waitcnt lgkmcnt(3)
	v_mfma_f32_32x32x16_bf16 v[80:95], v[208:211], v[120:123], v[80:95]
	s_waitcnt lgkmcnt(2)
	v_mfma_f32_32x32x16_bf16 v[64:79], v[212:215], v[120:123], v[64:79]
	s_waitcnt lgkmcnt(1)
	v_mfma_f32_32x32x16_bf16 v[80:95], v[216:219], v[124:127], v[80:95]
	s_waitcnt lgkmcnt(0)
	v_mfma_f32_32x32x16_bf16 v[64:79], v[220:223], v[124:127], v[64:79]
	v_mov_b32_e32 v149, v193
	v_mov_b32_e32 v150, v133
	v_mov_b32_e32 v151, v132
	s_nop 0
	v_lshlrev_b32_e32 v149, 2, v149
	v_sub_u32_e32 v155, v149, v150
	v_sub_u32_e32 v150, s6, v151
	v_add_u32_e32 v149, v150, v149
	v_and_b32_e32 v162, -16, v155
	v_add_u32_e32 v154, 0xe8, v149
	v_add_u32_e32 v149, 0x108, v149
	v_cmp_eq_u32_e32 vcc, s8, v162
	v_cmp_gt_u32_e64 s[6:7], 16, v155
	v_cndmask_b32_e32 v149, 0, v149, vcc
	v_lshl_add_u32 v149, v149, 2, 0
	v_add_u32_e32 v149, 0x18800, v149
	ds_read_b32 v152, v149
	v_mov_b32_e32 v149, 0xff800000
	v_mov_b32_e32 v150, 0xff800000
	s_and_saveexec_b64 s[8:9], s[6:7]
	s_cbranch_execz .LBB0_1700
	v_lshl_add_u32 v150, v154, 2, 0
	v_add_u32_e32 v150, 0x18800, v150
	ds_read_b32 v150, v150
	s_waitcnt lgkmcnt(0)
	v_add_f32_e32 v150, v80, v150

; __device__ __forceinline__ void finishSM(f32x16& p0, f32x16& p1, float alpha, float& l_reg, bf16x8& pa0, bf16x8& pa1, bf16x8& pa2, bf16x8& pa3) {
; #pragma unroll
;   for (int r = 0; r < 16; ++r) p1[r] = __builtin_amdgcn_exp2f(p1[r]);
;   float ps = 0;
; #pragma unroll
;   for (int r = 0; r < 16; ++r) ps += p0[r];
; #pragma unroll
;   for (int r = 0; r < 16; ++r) ps += p1[r];
;   { auto rr = __builtin_amdgcn_permlane32_swap(__float_as_uint(ps), __float_as_uint(ps), false, false);
;     ps = __uint_as_float(rr[0]) + __uint_as_float(rr[1]); }
;   l_reg = l_reg * alpha + ps;
;     ...
;   PK4(p0, 0, pa0); PK4(p0, 8, pa1); PK4(p1, 0, pa2); PK4(p1, 8, pa3);
; template <int D0> __device__ __forceinline__ void pv_one(f32x16& od, int vb, bf16x8 pa0, bf16x8 pa1, bf16x8 pa2, bf16x8 pa3) {
;   s16x4 l0 = tr_read<v_rd_off(D0, 0, 0)>(vb), h0 = tr_read<v_rd_off(D0, 0, 1)>(vb), l1 = tr_read<v_rd_off(D0, 1, 0)>(vb), h1 = tr_read<v_rd_off(D0, 1, 1)>(vb);
;   s16x4 l2 = tr_read<v_rd_off(D0, 2, 0)>(vb), h2 = tr_read<v_rd_off(D0, 2, 1)>(vb), l3 = tr_read<v_rd_off(D0, 3, 0)>(vb), h3 = tr_read<v_rd_off(D0, 3, 1)>(vb);
;   asm volatile("s_waitcnt lgkmcnt(0)" : "+v"(l0), "+v"(h0), "+v"(l1), "+v"(h1), "+v"(l2), "+v"(h2), "+v"(l3), "+v"(h3) :: "memory");
;     ...
;   od = __builtin_amdgcn_mfma_f32_32x32x16_bf16(pa0, PK(l0, h0), od, 0, 0, 0);
;   od = __builtin_amdgcn_mfma_f32_32x32x16_bf16(pa1, PK(l1, h1), od, 0, 0, 0);
;   od = __builtin_amdgcn_mfma_f32_32x32x16_bf16(pa2, PK(l2, h2), od, 0, 0, 0);
;   od = __builtin_amdgcn_mfma_f32_32x32x16_bf16(pa3, PK(l3, h3), od, 0, 0, 0);
;     ...
; }
; __device__ __forceinline__ void pv_d0(f32x16* o, int vb, bf16x8 pa0, bf16x8 pa1, bf16x8 pa2, bf16x8 pa3) {
;   pv_one<0>(o[0], vb, pa0, pa1, pa2, pa3); pv_one<1>(o[1], vb, pa0, pa1, pa2, pa3); pv_one<2>(o[2], vb, pa0, pa1, pa2, pa3); pv_one<3>(o[3], vb, pa0, pa1, pa2, pa3);
.LBB0_1735:
	v_mul_f32_e32 v79, 0xbe0293ee, v148
	v_fmamk_f32 v95, v150, 0x3e0293ee, v79
	v_fmamk_f32 v149, v149, 0x3e0293ee, v79
	v_fmamk_f32 v81, v81, 0x3e0293ee, v79
	v_fmamk_f32 v80, v80, 0x3e0293ee, v79
	v_fmamk_f32 v150, v151, 0x3e0293ee, v79
	v_fmamk_f32 v83, v83, 0x3e0293ee, v79
	v_fmamk_f32 v85, v85, 0x3e0293ee, v79
	v_fmamk_f32 v84, v84, 0x3e0293ee, v79
	v_fmamk_f32 v87, v87, 0x3e0293ee, v79
	v_fmamk_f32 v86, v86, 0x3e0293ee, v79
	v_fmamk_f32 v89, v89, 0x3e0293ee, v79
	v_fmamk_f32 v88, v88, 0x3e0293ee, v79
	v_fmamk_f32 v91, v91, 0x3e0293ee, v79
	v_fmamk_f32 v90, v90, 0x3e0293ee, v79
	v_fmamk_f32 v93, v93, 0x3e0293ee, v79
	v_fmamk_f32 v92, v92, 0x3e0293ee, v79
	v_fmamk_f32 v94, v94, 0x3e0293ee, v79
	v_fmamk_f32 v65, v65, 0x3e0293ee, v79
	v_fmamk_f32 v66, v66, 0x3e0293ee, v79
	v_fmamk_f32 v67, v67, 0x3e0293ee, v79
	v_fmamk_f32 v68, v68, 0x3e0293ee, v79
	v_fmamk_f32 v69, v69, 0x3e0293ee, v79
	v_fmamk_f32 v70, v70, 0x3e0293ee, v79
	v_fmamk_f32 v71, v71, 0x3e0293ee, v79
	v_fmamk_f32 v72, v72, 0x3e0293ee, v79
	v_fmamk_f32 v73, v73, 0x3e0293ee, v79
	v_fmamk_f32 v74, v74, 0x3e0293ee, v79
	v_fmamk_f32 v75, v75, 0x3e0293ee, v79
	v_fmamk_f32 v76, v76, 0x3e0293ee, v79
	v_fmamk_f32 v77, v77, 0x3e0293ee, v79
	v_fmamk_f32 v78, v78, 0x3e0293ee, v79
	v_fmac_f32_e32 v79, 0x3e0293ee, v64
	v_exp_f32_e32 v154, v95
	v_exp_f32_e32 v149, v149
	v_exp_f32_e32 v81, v81
	v_exp_f32_e32 v80, v80
	v_exp_f32_e32 v155, v150
	v_exp_f32_e32 v83, v83
	v_exp_f32_e32 v156, v85
	v_exp_f32_e32 v157, v84
	v_exp_f32_e32 v158, v87
	v_exp_f32_e32 v159, v86
	v_exp_f32_e32 v160, v89
	v_exp_f32_e32 v161, v88
	v_exp_f32_e32 v162, v91
	v_exp_f32_e32 v163, v90
	v_exp_f32_e32 v164, v93
	v_exp_f32_e32 v165, v92
	v_exp_f32_e32 v166, v94
	v_exp_f32_e32 v167, v65
	v_exp_f32_e32 v168, v66
	v_exp_f32_e32 v169, v67
	v_exp_f32_e32 v170, v68
	v_exp_f32_e32 v171, v69
	v_exp_f32_e32 v172, v70
	v_exp_f32_e32 v173, v71
	v_exp_f32_e32 v174, v72
	v_exp_f32_e32 v175, v73
	v_exp_f32_e32 v176, v74
	v_exp_f32_e32 v177, v75
	v_exp_f32_e32 v178, v76
	v_exp_f32_e32 v179, v77
	v_exp_f32_e32 v180, v78
	v_exp_f32_e32 v181, v79
	v_cvt_pk_bf16_f32 v64, v154, v149
	v_cvt_pk_bf16_f32 v65, v81, v80
	v_cvt_pk_bf16_f32 v66, v155, v83
	v_cvt_pk_bf16_f32 v67, v156, v157
	v_cvt_pk_bf16_f32 v68, v158, v159
	v_cvt_pk_bf16_f32 v69, v160, v161
	v_cvt_pk_bf16_f32 v70, v162, v163
	v_cvt_pk_bf16_f32 v71, v164, v165
	v_cvt_pk_bf16_f32 v72, v166, v167
	v_cvt_pk_bf16_f32 v73, v168, v169
	v_cvt_pk_bf16_f32 v74, v170, v171
	v_cvt_pk_bf16_f32 v75, v172, v173
	v_cvt_pk_bf16_f32 v76, v174, v175
	v_cvt_pk_bf16_f32 v77, v176, v177
	v_cvt_pk_bf16_f32 v78, v178, v179
	v_cvt_pk_bf16_f32 v79, v180, v181
	v_add_u32_e32 v182, s73, v146
	ds_read_b64_tr_b16 v[84:85], v182 offset:0
	ds_read_b64_tr_b16 v[86:87], v182 offset:0x800
	ds_read_b64_tr_b16 v[88:89], v182 offset:0x1000
	v_permlane32_swap_b32_e32 v64, v66
	v_permlane32_swap_b32_e32 v65, v67
	ds_read_b64_tr_b16 v[90:91], v182 offset:0x1800
	ds_read_b64_tr_b16 v[92:93], v182 offset:0x2000
	ds_read_b64_tr_b16 v[94:95], v182 offset:0x2800
	ds_read_b64_tr_b16 v[150:151], v182 offset:0x3000
	ds_read_b64_tr_b16 v[152:153], v182 offset:0x3800
	v_permlane32_swap_b32_e32 v68, v70
	s_waitcnt lgkmcnt(0)
	v_permlane32_swap_b32_e32 v69, v71
	v_mfma_f32_32x32x16_bf16 v[0:15], v[64:67], v[84:87], v[0:15]
	v_permlane32_swap_b32_e32 v72, v74
	v_permlane32_swap_b32_e32 v73, v75
	ds_read_b64_tr_b16 v[84:85], v182 offset:0x200
	v_permlane32_swap_b32_e32 v76, v78
	v_mfma_f32_32x32x16_bf16 v[0:15], v[68:71], v[88:91], v[0:15]
	v_permlane32_swap_b32_e32 v77, v79
	ds_read_b64_tr_b16 v[86:87], v182 offset:0xa00
	ds_read_b64_tr_b16 v[88:89], v182 offset:0x1200
	ds_read_b64_tr_b16 v[90:91], v182 offset:0x1a00
	v_mfma_f32_32x32x16_bf16 v[0:15], v[72:75], v[92:95], v[0:15]
	ds_read_b64_tr_b16 v[92:93], v182 offset:0x2200
	ds_read_b64_tr_b16 v[94:95], v182 offset:0x2a00
	s_nop 0
	v_mfma_f32_32x32x16_bf16 v[0:15], v[76:79], v[150:153], v[0:15]
	ds_read_b64_tr_b16 v[150:151], v182 offset:0x3200
	ds_read_b64_tr_b16 v[152:153], v182 offset:0x3a00
	s_nop 0
	s_waitcnt lgkmcnt(0)
	s_nop 0
	v_mfma_f32_32x32x16_bf16 v[48:63], v[64:67], v[84:87], v[48:63]
	ds_read_b64_tr_b16 v[84:85], v182 offset:0x400
	ds_read_b64_tr_b16 v[86:87], v182 offset:0xc00
	v_mfma_f32_32x32x16_bf16 v[48:63], v[68:71], v[88:91], v[48:63]
	ds_read_b64_tr_b16 v[88:89], v182 offset:0x1400
	ds_read_b64_tr_b16 v[90:91], v182 offset:0x1c00
	v_mfma_f32_32x32x16_bf16 v[48:63], v[72:75], v[92:95], v[48:63]
	ds_read_b64_tr_b16 v[92:93], v182 offset:0x2400
	ds_read_b64_tr_b16 v[94:95], v182 offset:0x2c00
	v_mfma_f32_32x32x16_bf16 v[48:63], v[76:79], v[150:153], v[48:63]
	ds_read_b64_tr_b16 v[150:151], v182 offset:0x3400
	ds_read_b64_tr_b16 v[152:153], v182 offset:0x3c00
	s_nop 0
	s_waitcnt lgkmcnt(0)
	s_nop 0
	v_mfma_f32_32x32x16_bf16 v[32:47], v[64:67], v[84:87], v[32:47]
	v_add_f32_e32 v84, 0, v154
	v_add_f32_e32 v84, v149, v84
	v_add_f32_e32 v81, v81, v84
	ds_read_b64_tr_b16 v[84:85], v182 offset:0x600
	ds_read_b64_tr_b16 v[86:87], v182 offset:0xe00
	v_add_f32_e32 v80, v80, v81
	v_add_f32_e32 v80, v155, v80
	v_mfma_f32_32x32x16_bf16 v[32:47], v[68:71], v[88:91], v[32:47]
	ds_read_b64_tr_b16 v[88:89], v182 offset:0x1600
	ds_read_b64_tr_b16 v[90:91], v182 offset:0x1e00
	v_add_f32_e32 v80, v83, v80
	v_add_f32_e32 v80, v156, v80
	v_add_f32_e32 v80, v157, v80
	v_add_f32_e32 v80, v158, v80
	v_add_f32_e32 v80, v159, v80
	v_mfma_f32_32x32x16_bf16 v[32:47], v[72:75], v[92:95], v[32:47]
	ds_read_b64_tr_b16 v[92:93], v182 offset:0x2600
	ds_read_b64_tr_b16 v[94:95], v182 offset:0x2e00
	v_add_f32_e32 v80, v160, v80
	v_add_f32_e32 v80, v161, v80
	v_add_f32_e32 v80, v162, v80
	v_add_f32_e32 v80, v163, v80
	v_add_f32_e32 v80, v164, v80
	v_mfma_f32_32x32x16_bf16 v[32:47], v[76:79], v[150:153], v[32:47]
	ds_read_b64_tr_b16 v[150:151], v182 offset:0x3600
	ds_read_b64_tr_b16 v[152:153], v182 offset:0x3e00
	v_add_f32_e32 v80, v165, v80
	s_waitcnt lgkmcnt(0)
	s_nop 0
	v_mfma_f32_32x32x16_bf16 v[16:31], v[64:67], v[84:87], v[16:31]
	v_add_f32_e32 v64, v166, v80
	v_add_f32_e32 v64, v167, v64
	v_add_f32_e32 v64, v168, v64
	v_add_f32_e32 v64, v169, v64
	v_add_f32_e32 v64, v170, v64
	v_add_f32_e32 v64, v171, v64
	v_add_f32_e32 v64, v172, v64
	v_mfma_f32_32x32x16_bf16 v[16:31], v[68:71], v[88:91], v[16:31]
	v_add_f32_e32 v64, v173, v64
	v_add_f32_e32 v64, v174, v64
	v_add_f32_e32 v64, v175, v64
	v_add_f32_e32 v64, v176, v64
	v_add_f32_e32 v64, v177, v64
	v_add_f32_e32 v64, v178, v64
	v_add_f32_e32 v64, v179, v64
	v_mfma_f32_32x32x16_bf16 v[16:31], v[72:75], v[92:95], v[16:31]
	v_add_f32_e32 v64, v180, v64
	v_add_f32_e32 v64, v181, v64
	v_mov_b32_e32 v65, v64
	s_nop 1
	v_permlane32_swap_b32_e32 v64, v65
	v_add_f32_e32 v64, v64, v65
	v_fmac_f32_e32 v64, v147, v82
	v_mfma_f32_32x32x16_bf16 v[16:31], v[76:79], v[150:153], v[16:31]
	v_mov_b32_e32 v147, v64
.LBB0_1736:
	s_cmp_eq_u32 s42, s70
	s_cbranch_scc1 .LBB0_1739
	s_mov_b32 s16, s42
	s_add_i32 s98, s98, 1
	s_cmp_eq_u32 s98, 3
	s_cselect_b32 s98, 0, s98
	s_branch .LBB0_1691

; #define LAS __attribute__((address_space(3)))
; __global__ void __launch_bounds__(NWAVES * 64, 2) fwd_kernel(Args a) {
;     extern __shared__ __attribute__((aligned(16))) unsigned char lds_raw[];
;     LAS unsigned char* lds = (LAS unsigned char*)lds_raw;
;     const int tid = threadIdx.x, lane = tid & 63, wave = __builtin_amdgcn_readfirstlane(tid >> 6);
	.amdhsa_kernel _Z10fwd_kernel4Args
		.amdhsa_group_segment_fixed_size 0
		.amdhsa_private_segment_fixed_size 0
		.amdhsa_kernarg_size 440
		.amdhsa_user_sgpr_count 2
		.amdhsa_user_sgpr_dispatch_ptr 0
		.amdhsa_user_sgpr_queue_ptr 0
		.amdhsa_user_sgpr_kernarg_segment_ptr 1
		.amdhsa_user_sgpr_dispatch_id 0
		.amdhsa_user_sgpr_kernarg_preload_length 0
		.amdhsa_user_sgpr_kernarg_preload_offset 0
		.amdhsa_user_sgpr_private_segment_size 0
		.amdhsa_uses_dynamic_stack 0
		.amdhsa_enable_private_segment 0
		.amdhsa_system_sgpr_workgroup_id_x 1
		.amdhsa_system_sgpr_workgroup_id_y 0
		.amdhsa_system_sgpr_workgroup_id_z 0
		.amdhsa_system_sgpr_workgroup_info 0
		.amdhsa_system_vgpr_workitem_id 2
		.amdhsa_next_free_vgpr 249
		.amdhsa_next_free_sgpr 102
		.amdhsa_accum_offset 252
		.amdhsa_reserve_vcc 1
		.amdhsa_float_round_mode_32 0
		.amdhsa_float_round_mode_16_64 0
		.amdhsa_float_denorm_mode_32 3
		.amdhsa_float_denorm_mode_16_64 3
		.amdhsa_dx10_clamp 1
		.amdhsa_ieee_mode 1
		.amdhsa_fp16_overflow 0
		.amdhsa_tg_split 0
		.amdhsa_exception_fp_ieee_invalid_op 0
		.amdhsa_exception_fp_denorm_src 0
		.amdhsa_exception_fp_ieee_div_zero 0
		.amdhsa_exception_fp_ieee_overflow 0
		.amdhsa_exception_fp_ieee_underflow 0
		.amdhsa_exception_fp_ieee_inexact 0
		.amdhsa_exception_int_div_zero 0
	.end_amdhsa_kernel

; #define LAS __attribute__((address_space(3)))
; __global__ void __launch_bounds__(NWAVES * 64, 2) fwd_kernel(Args a) {
;     extern __shared__ __attribute__((aligned(16))) unsigned char lds_raw[];
;     LAS unsigned char* lds = (LAS unsigned char*)lds_raw;
;     const int tid = threadIdx.x, lane = tid & 63, wave = __builtin_amdgcn_readfirstlane(tid >> 6);
amdhsa.kernels:
  - .agpr_count:     0
    .args:
      - .offset:         0
        .size:           184
        .value_kind:     by_value
      - .offset:         184
        .size:           4
        .value_kind:     hidden_block_count_x
      - .offset:         188
        .size:           4
        .value_kind:     hidden_block_count_y
      - .offset:         192
        .size:           4
        .value_kind:     hidden_block_count_z
      - .offset:         196
        .size:           2
        .value_kind:     hidden_group_size_x
      - .offset:         198
        .size:           2
        .value_kind:     hidden_group_size_y
      - .offset:         200
        .size:           2
        .value_kind:     hidden_group_size_z
      - .offset:         202
        .size:           2
        .value_kind:     hidden_remainder_x
      - .offset:         204
        .size:           2
        .value_kind:     hidden_remainder_y
      - .offset:         206
        .size:           2
        .value_kind:     hidden_remainder_z
      - .offset:         224
        .size:           8
        .value_kind:     hidden_global_offset_x
      - .offset:         232
        .size:           8
        .value_kind:     hidden_global_offset_y
      - .offset:         240
        .size:           8
        .value_kind:     hidden_global_offset_z
      - .offset:         248
        .size:           2
        .value_kind:     hidden_grid_dims
      - .offset:         272
        .size:           8
        .value_kind:     hidden_multigrid_sync_arg
      - .offset:         304
        .size:           4
        .value_kind:     hidden_dynamic_lds_size
    .group_segment_fixed_size: 0
    .kernarg_segment_align: 8
    .kernarg_segment_size: 440
    .language:       OpenCL C
    .language_version:
      - 2
      - 0
    .max_flat_workgroup_size: 512
    .name:           _Z10fwd_kernel4Args
    .private_segment_fixed_size: 0
    .sgpr_count:     108
    .sgpr_spill_count: 82
    .symbol:         _Z10fwd_kernel4Args.kd
    .uniform_work_group_size: 1
    .uses_dynamic_stack: false
    .vgpr_count:     249
    .vgpr_spill_count: 0
    .wavefront_size: 64
